# removed per-section s_setprio flips in all GEMM MFMA sections
# speedup vs baseline: 1.0232x; 1.0007x over previous
; #define PG8_STAGE(bufoff, gbase, voff) do { _Pragma("unroll") for (int _i = 0; _i < 2; ++_i) \
;         __builtin_amdgcn_global_load_lds((const unsigned*)((const char*)(gbase) + (voff)[_i]), (LAS unsigned*)(lds + (bufoff) + ldsw + _i * 8192), 16, 0, 0); } while (0)
; #define PG8_LDA(dst, b, h) do { _Pragma("unroll") for (int m = 0; m < 4; ++m) _Pragma("unroll") for (int k = 0; k < 2; ++k) dst[m][k] = *(const LAS bf16x8*)(lds + PG8_SA(b, h) + aoff + m * 2048 + k * 1024); } while (0)
; #define PG8_LDB(dst, b, h) do { _Pragma("unroll") for (int n = 0; n < 2; ++n) _Pragma("unroll") for (int k = 0; k < 2; ++k) dst[n][k] = *(const LAS bf16x8*)(lds + PG8_SB(b, h) + boff + n * 2048 + k * 1024); } while (0)
; #define PG8_MMA(ai, bj, At, Bt) do { __builtin_amdgcn_s_setprio(1); _Pragma("unroll") for (int m = 0; m < 4; ++m) _Pragma("unroll") for (int n = 0; n < 2; ++n) _Pragma("unroll") for (int k = 0; k < 2; ++k) \
;         acc[ai][bj][m][n] = __builtin_amdgcn_mfma_f32_16x16x32_bf16(Bt[n][k], At[m][k], acc[ai][bj][m][n], 0, 0, 0); __builtin_amdgcn_s_setprio(0); } while (0)
; #define PG8_WAIT_V(n) asm volatile("s_waitcnt vmcnt(" #n ")" ::: "memory")
; #define PG8_WAIT_L(n) asm volatile("s_waitcnt lgkmcnt(" #n ")" ::: "memory")
; #define PG8_BAR __builtin_amdgcn_s_barrier()
; #define PG8_SCHED __builtin_amdgcn_sched_barrier(0)
; template <class Epi>
; __device__ __forceinline__ void gemm_phase(LAS unsigned char* lds, const Gemm g, const StaticOrder& S, const Epi& E, const int tid) {
;     ...
;         for (int t = 0; t < nt; t += 2) {
;             const bool last = (t == nt - 2);
;             const char* a1 = cA + (size_t)(t + 1) * kstepA;
;             const char* a2 = last ? nA : cA + (size_t)(t + 2) * kstepA; const char* b2 = last ? nB : cB + (size_t)(t + 2) * kstep;
;             const char* a3 = a2 + kstepA; const char* b3 = b2 + kstep;
;             PG8_LDB(B0, 0, 0); PG8_LDB(B1, 0, 1); PG8_SCHED; PG8_LDA(At, 0, 0); PG8_STAGE(PG8_SA(1, 1), a1 + hstepA, voffA);
;             PG8_WAIT_V(8); PG8_WAIT_L(0); PG8_BAR; PG8_MMA(0, 0, At, B0); PG8_MMA(0, 1, At, B1); PG8_BAR; PG8_SCHED;
;             PG8_LDA(At, 0, 1); PG8_STAGE(PG8_SB(0, 0), b2, voffB); PG8_STAGE(PG8_SB(0, 1), b2 + hstepB, voffB); PG8_STAGE(PG8_SA(0, 0), a2, voffA);
.LBB0_225:
	s_add_u32 s28, s16, 0x1000
	s_addc_u32 s29, s17, 0
	s_add_i32 s52, 0, 0x10000
	s_cmp_eq_u32 s51, 12
	s_cselect_b32 s41, s11, s29
	s_cselect_b32 s40, s47, s28
	s_cselect_b32 s35, s9, s50
	s_cselect_b32 s34, s48, s49
	s_add_i32 s53, 0, 0x14000
	v_add_u32_e32 v140, s52, v175
	v_add_u32_e32 v164, s53, v175
	ds_read_b128 v[128:131], v140
	ds_read_b128 v[132:135], v140 offset:1024
	ds_read_b128 v[136:139], v140 offset:2048
	ds_read_b128 v[140:143], v140 offset:3072
	ds_read_b128 v[156:159], v164
	ds_read_b128 v[160:163], v164 offset:1024
	ds_read_b128 v[168:171], v164 offset:2048
	ds_read_b128 v[178:181], v164 offset:3072
	v_lshl_add_u64 v[164:165], s[16:17], 0, v[152:153]
	s_add_i32 m0, s21, 0xc000
	ds_read_b128 v[202:205], v196
	ds_read_b128 v[206:209], v196 offset:1024
	ds_read_b128 v[210:213], v196 offset:2048
	ds_read_b128 v[214:217], v196 offset:3072
	ds_read_b128 v[226:229], v196 offset:4096
	ds_read_b128 v[230:233], v196 offset:5120
	ds_read_b128 v[234:237], v196 offset:6144
	ds_read_b128 v[238:241], v196 offset:7168
	global_load_lds_dwordx4 v[164:165], off
	v_lshl_add_u64 v[164:165], s[16:17], 0, v[154:155]
	s_add_i32 m0, s21, 0xe000
	s_nop 0
	global_load_lds_dwordx4 v[164:165], off
	s_waitcnt vmcnt(8)
	s_waitcnt lgkmcnt(0)
	s_barrier
	v_mfma_f32_16x16x32_bf16 v[124:127], v[128:131], v[202:205], v[124:127]
	v_mfma_f32_16x16x32_bf16 v[120:123], v[136:139], v[202:205], v[120:123]
	v_mfma_f32_16x16x32_bf16 v[116:119], v[128:131], v[210:213], v[116:119]
	v_mfma_f32_16x16x32_bf16 v[108:111], v[136:139], v[210:213], v[108:111]
	v_mfma_f32_16x16x32_bf16 v[100:103], v[128:131], v[226:229], v[100:103]
	v_mfma_f32_16x16x32_bf16 v[92:95], v[136:139], v[226:229], v[92:95]
	v_mfma_f32_16x16x32_bf16 v[84:87], v[128:131], v[234:237], v[84:87]
	v_mfma_f32_16x16x32_bf16 v[76:79], v[136:139], v[234:237], v[76:79]
	v_mfma_f32_16x16x32_bf16 v[124:127], v[132:135], v[206:209], v[124:127]
	v_mfma_f32_16x16x32_bf16 v[120:123], v[140:143], v[206:209], v[120:123]
	v_mfma_f32_16x16x32_bf16 v[116:119], v[132:135], v[214:217], v[116:119]
	v_mfma_f32_16x16x32_bf16 v[108:111], v[140:143], v[214:217], v[108:111]
	v_mfma_f32_16x16x32_bf16 v[100:103], v[132:135], v[230:233], v[100:103]
	v_mfma_f32_16x16x32_bf16 v[92:95], v[140:143], v[230:233], v[92:95]
	v_mfma_f32_16x16x32_bf16 v[84:87], v[132:135], v[238:241], v[84:87]
	v_mfma_f32_16x16x32_bf16 v[76:79], v[140:143], v[238:241], v[76:79]
	v_mfma_f32_16x16x32_bf16 v[112:115], v[156:159], v[202:205], v[112:115]
	v_mfma_f32_16x16x32_bf16 v[104:107], v[168:171], v[202:205], v[104:107]
	v_mfma_f32_16x16x32_bf16 v[96:99], v[156:159], v[210:213], v[96:99]
	v_mfma_f32_16x16x32_bf16 v[88:91], v[168:171], v[210:213], v[88:91]
	v_mfma_f32_16x16x32_bf16 v[80:83], v[156:159], v[226:229], v[80:83]
	v_mfma_f32_16x16x32_bf16 v[72:75], v[168:171], v[226:229], v[72:75]
	v_mfma_f32_16x16x32_bf16 v[68:71], v[156:159], v[234:237], v[68:71]
	v_mfma_f32_16x16x32_bf16 v[64:67], v[168:171], v[234:237], v[64:67]
	v_mfma_f32_16x16x32_bf16 v[112:115], v[160:163], v[206:209], v[112:115]
	v_mfma_f32_16x16x32_bf16 v[104:107], v[178:181], v[206:209], v[104:107]
	v_mfma_f32_16x16x32_bf16 v[96:99], v[160:163], v[214:217], v[96:99]
	v_mfma_f32_16x16x32_bf16 v[88:91], v[178:181], v[214:217], v[88:91]
	v_mfma_f32_16x16x32_bf16 v[80:83], v[160:163], v[230:233], v[80:83]
	v_mfma_f32_16x16x32_bf16 v[72:75], v[178:181], v[230:233], v[72:75]
	v_mfma_f32_16x16x32_bf16 v[68:71], v[160:163], v[238:241], v[68:71]
	v_mfma_f32_16x16x32_bf16 v[64:67], v[178:181], v[238:241], v[64:67]
	s_barrier
	s_add_i32 s16, s52, s20
	v_lshl_add_u64 v[164:165], s[34:35], 0, v[176:177]
	s_mov_b32 m0, s16
	ds_read_b128 v[202:205], v196 offset:16384
	ds_read_b128 v[206:209], v196 offset:17408
	ds_read_b128 v[210:213], v196 offset:18432
	ds_read_b128 v[214:217], v196 offset:19456
	ds_read_b128 v[226:229], v196 offset:20480
	ds_read_b128 v[230:233], v196 offset:21504
	ds_read_b128 v[234:237], v196 offset:22528
	ds_read_b128 v[238:241], v196 offset:23552
	global_load_lds_dwordx4 v[164:165], off
	s_add_i32 m0, s16, 0x2000
	s_add_u32 s16, s34, 0x40000
	v_lshl_add_u64 v[172:173], s[34:35], 0, v[144:145]
	s_addc_u32 s17, s35, 0
	s_add_i32 s52, s53, s20
	global_load_lds_dwordx4 v[172:173], off
	v_lshl_add_u64 v[194:195], s[16:17], 0, v[176:177]
	s_mov_b32 m0, s52
	v_lshl_add_u64 v[198:199], s[40:41], 0, v[146:147]
	global_load_lds_dwordx4 v[194:195], off
	v_lshl_add_u64 v[194:195], s[16:17], 0, v[144:145]
	s_add_i32 m0, s52, 0x2000
	s_nop 0
	global_load_lds_dwordx4 v[194:195], off
	v_lshl_add_u64 v[194:195], s[40:41], 0, v[148:149]
	s_mov_b32 m0, s21
	s_nop 0
	global_load_lds_dwordx4 v[194:195], off
	s_mov_b32 m0, s22
	s_nop 0
	global_load_lds_dwordx4 v[198:199], off
	s_waitcnt vmcnt(8)
	s_waitcnt lgkmcnt(0)
	s_barrier
; #define PG8_STAGE(bufoff, gbase, voff) do { _Pragma("unroll") for (int _i = 0; _i < 2; ++_i) \
;         __builtin_amdgcn_global_load_lds((const unsigned*)((const char*)(gbase) + (voff)[_i]), (LAS unsigned*)(lds + (bufoff) + ldsw + _i * 8192), 16, 0, 0); } while (0)
; #define PG8_LDA(dst, b, h) do { _Pragma("unroll") for (int m = 0; m < 4; ++m) _Pragma("unroll") for (int k = 0; k < 2; ++k) dst[m][k] = *(const LAS bf16x8*)(lds + PG8_SA(b, h) + aoff + m * 2048 + k * 1024); } while (0)
; #define PG8_LDB(dst, b, h) do { _Pragma("unroll") for (int n = 0; n < 2; ++n) _Pragma("unroll") for (int k = 0; k < 2; ++k) dst[n][k] = *(const LAS bf16x8*)(lds + PG8_SB(b, h) + boff + n * 2048 + k * 1024); } while (0)
; #define PG8_MMA(ai, bj, At, Bt) do { __builtin_amdgcn_s_setprio(1); _Pragma("unroll") for (int m = 0; m < 4; ++m) _Pragma("unroll") for (int n = 0; n < 2; ++n) _Pragma("unroll") for (int k = 0; k < 2; ++k) \
;         acc[ai][bj][m][n] = __builtin_amdgcn_mfma_f32_16x16x32_bf16(Bt[n][k], At[m][k], acc[ai][bj][m][n], 0, 0, 0); __builtin_amdgcn_s_setprio(0); } while (0)
; #define PG8_WAIT_V(n) asm volatile("s_waitcnt vmcnt(" #n ")" ::: "memory")
; #define PG8_WAIT_L(n) asm volatile("s_waitcnt lgkmcnt(" #n ")" ::: "memory")
; #define PG8_BAR __builtin_amdgcn_s_barrier()
; #define PG8_SCHED __builtin_amdgcn_sched_barrier(0)
; template <class Epi>
; __device__ __forceinline__ void gemm_phase(LAS unsigned char* lds, const Gemm g, const StaticOrder& S, const Epi& E, const int tid) {
;     ...
;             PG8_WAIT_V(8); PG8_WAIT_L(0); PG8_BAR; PG8_MMA(1, 0, At, B0); PG8_MMA(1, 1, At, B1); PG8_BAR; PG8_SCHED;
;             PG8_LDB(B0, 1, 0); PG8_LDB(B1, 1, 1); PG8_SCHED; PG8_LDA(At, 1, 0); PG8_STAGE(PG8_SA(0, 1), a2 + hstepA, voffA);
;             PG8_WAIT_V(8); PG8_WAIT_L(0); PG8_BAR; PG8_MMA(0, 0, At, B0); PG8_MMA(0, 1, At, B1); PG8_BAR; PG8_SCHED;
	v_mfma_f32_16x16x32_bf16 v[60:63], v[128:131], v[202:205], v[60:63]
	v_mfma_f32_16x16x32_bf16 v[56:59], v[136:139], v[202:205], v[56:59]
	v_mfma_f32_16x16x32_bf16 v[52:55], v[128:131], v[210:213], v[52:55]
	v_mfma_f32_16x16x32_bf16 v[44:47], v[136:139], v[210:213], v[44:47]
	v_mfma_f32_16x16x32_bf16 v[36:39], v[128:131], v[226:229], v[36:39]
	v_mfma_f32_16x16x32_bf16 v[28:31], v[136:139], v[226:229], v[28:31]
	v_mfma_f32_16x16x32_bf16 v[20:23], v[128:131], v[234:237], v[20:23]
	v_mfma_f32_16x16x32_bf16 v[12:15], v[136:139], v[234:237], v[12:15]
	v_mfma_f32_16x16x32_bf16 v[60:63], v[132:135], v[206:209], v[60:63]
	v_mfma_f32_16x16x32_bf16 v[56:59], v[140:143], v[206:209], v[56:59]
	v_mfma_f32_16x16x32_bf16 v[52:55], v[132:135], v[214:217], v[52:55]
	v_mfma_f32_16x16x32_bf16 v[44:47], v[140:143], v[214:217], v[44:47]
	v_mfma_f32_16x16x32_bf16 v[36:39], v[132:135], v[230:233], v[36:39]
	v_mfma_f32_16x16x32_bf16 v[28:31], v[140:143], v[230:233], v[28:31]
	v_mfma_f32_16x16x32_bf16 v[20:23], v[132:135], v[238:241], v[20:23]
	v_mfma_f32_16x16x32_bf16 v[12:15], v[140:143], v[238:241], v[12:15]
	v_mfma_f32_16x16x32_bf16 v[48:51], v[156:159], v[202:205], v[48:51]
	v_mfma_f32_16x16x32_bf16 v[40:43], v[168:171], v[202:205], v[40:43]
	v_mfma_f32_16x16x32_bf16 v[32:35], v[156:159], v[210:213], v[32:35]
	v_mfma_f32_16x16x32_bf16 v[24:27], v[168:171], v[210:213], v[24:27]
	v_mfma_f32_16x16x32_bf16 v[16:19], v[156:159], v[226:229], v[16:19]
	v_mfma_f32_16x16x32_bf16 v[8:11], v[168:171], v[226:229], v[8:11]
	v_mfma_f32_16x16x32_bf16 v[4:7], v[156:159], v[234:237], v[4:7]
	v_mfma_f32_16x16x32_bf16 v[0:3], v[168:171], v[234:237], v[0:3]
	v_mfma_f32_16x16x32_bf16 v[48:51], v[160:163], v[206:209], v[48:51]
	v_mfma_f32_16x16x32_bf16 v[40:43], v[178:181], v[206:209], v[40:43]
	v_mfma_f32_16x16x32_bf16 v[32:35], v[160:163], v[214:217], v[32:35]
	v_mfma_f32_16x16x32_bf16 v[24:27], v[178:181], v[214:217], v[24:27]
	v_mfma_f32_16x16x32_bf16 v[16:19], v[160:163], v[230:233], v[16:19]
	v_mfma_f32_16x16x32_bf16 v[8:11], v[178:181], v[230:233], v[8:11]
	v_mfma_f32_16x16x32_bf16 v[4:7], v[160:163], v[238:241], v[4:7]
	v_mfma_f32_16x16x32_bf16 v[0:3], v[178:181], v[238:241], v[0:3]
	s_barrier
	s_add_i32 s52, 0, 0x18000
	s_add_i32 s53, 0, 0x1c000
	v_add_u32_e32 v140, s52, v175
	v_add_u32_e32 v166, s53, v175
	ds_read_b128 v[128:131], v140
	ds_read_b128 v[132:135], v140 offset:1024
	ds_read_b128 v[136:139], v140 offset:2048
	ds_read_b128 v[140:143], v140 offset:3072
	ds_read_b128 v[156:159], v166
	ds_read_b128 v[160:163], v166 offset:1024
	ds_read_b128 v[168:171], v166 offset:2048
	ds_read_b128 v[178:181], v166 offset:3072
	s_add_u32 s16, s40, 0x40000
	s_addc_u32 s17, s41, 0
	s_mov_b32 m0, s23
	v_lshl_add_u64 v[218:219], s[16:17], 0, v[148:149]
	ds_read_b128 v[202:205], v196 offset:32768
	ds_read_b128 v[206:209], v196 offset:33792
	ds_read_b128 v[210:213], v196 offset:34816
	ds_read_b128 v[214:217], v196 offset:35840
	ds_read_b128 v[226:229], v196 offset:36864
	ds_read_b128 v[230:233], v196 offset:37888
	ds_read_b128 v[234:237], v196 offset:38912
	ds_read_b128 v[238:241], v196 offset:39936
	global_load_lds_dwordx4 v[218:219], off
	v_lshl_add_u64 v[218:219], s[16:17], 0, v[146:147]
	s_mov_b32 m0, s30
	s_nop 0
	global_load_lds_dwordx4 v[218:219], off
	s_waitcnt vmcnt(8)
	s_waitcnt lgkmcnt(0)
	s_barrier
	v_mfma_f32_16x16x32_bf16 v[124:127], v[128:131], v[202:205], v[124:127]
	v_mfma_f32_16x16x32_bf16 v[120:123], v[136:139], v[202:205], v[120:123]
	v_mfma_f32_16x16x32_bf16 v[116:119], v[128:131], v[210:213], v[116:119]
	v_mfma_f32_16x16x32_bf16 v[108:111], v[136:139], v[210:213], v[108:111]
	v_mfma_f32_16x16x32_bf16 v[100:103], v[128:131], v[226:229], v[100:103]
	v_mfma_f32_16x16x32_bf16 v[92:95], v[136:139], v[226:229], v[92:95]
	v_mfma_f32_16x16x32_bf16 v[84:87], v[128:131], v[234:237], v[84:87]
	v_mfma_f32_16x16x32_bf16 v[76:79], v[136:139], v[234:237], v[76:79]
	v_mfma_f32_16x16x32_bf16 v[124:127], v[132:135], v[206:209], v[124:127]
	v_mfma_f32_16x16x32_bf16 v[120:123], v[140:143], v[206:209], v[120:123]
	v_mfma_f32_16x16x32_bf16 v[116:119], v[132:135], v[214:217], v[116:119]
	v_mfma_f32_16x16x32_bf16 v[108:111], v[140:143], v[214:217], v[108:111]
	v_mfma_f32_16x16x32_bf16 v[100:103], v[132:135], v[230:233], v[100:103]
	v_mfma_f32_16x16x32_bf16 v[92:95], v[140:143], v[230:233], v[92:95]
	v_mfma_f32_16x16x32_bf16 v[84:87], v[132:135], v[238:241], v[84:87]
	v_mfma_f32_16x16x32_bf16 v[76:79], v[140:143], v[238:241], v[76:79]
	v_mfma_f32_16x16x32_bf16 v[112:115], v[156:159], v[202:205], v[112:115]
	v_mfma_f32_16x16x32_bf16 v[104:107], v[168:171], v[202:205], v[104:107]
	v_mfma_f32_16x16x32_bf16 v[96:99], v[156:159], v[210:213], v[96:99]
	v_mfma_f32_16x16x32_bf16 v[88:91], v[168:171], v[210:213], v[88:91]
	v_mfma_f32_16x16x32_bf16 v[80:83], v[156:159], v[226:229], v[80:83]
	v_mfma_f32_16x16x32_bf16 v[72:75], v[168:171], v[226:229], v[72:75]
	v_mfma_f32_16x16x32_bf16 v[68:71], v[156:159], v[234:237], v[68:71]
	v_mfma_f32_16x16x32_bf16 v[64:67], v[168:171], v[234:237], v[64:67]
	v_mfma_f32_16x16x32_bf16 v[112:115], v[160:163], v[206:209], v[112:115]
	v_mfma_f32_16x16x32_bf16 v[104:107], v[178:181], v[206:209], v[104:107]
	v_mfma_f32_16x16x32_bf16 v[96:99], v[160:163], v[214:217], v[96:99]
	v_mfma_f32_16x16x32_bf16 v[88:91], v[178:181], v[214:217], v[88:91]
	v_mfma_f32_16x16x32_bf16 v[80:83], v[160:163], v[230:233], v[80:83]
	v_mfma_f32_16x16x32_bf16 v[72:75], v[178:181], v[230:233], v[72:75]
	v_mfma_f32_16x16x32_bf16 v[68:71], v[160:163], v[238:241], v[68:71]
	v_mfma_f32_16x16x32_bf16 v[64:67], v[178:181], v[238:241], v[64:67]
	s_barrier
; #define PG8_STAGE(bufoff, gbase, voff) do { _Pragma("unroll") for (int _i = 0; _i < 2; ++_i) \
;         __builtin_amdgcn_global_load_lds((const unsigned*)((const char*)(gbase) + (voff)[_i]), (LAS unsigned*)(lds + (bufoff) + ldsw + _i * 8192), 16, 0, 0); } while (0)
; #define PG8_LDA(dst, b, h) do { _Pragma("unroll") for (int m = 0; m < 4; ++m) _Pragma("unroll") for (int k = 0; k < 2; ++k) dst[m][k] = *(const LAS bf16x8*)(lds + PG8_SA(b, h) + aoff + m * 2048 + k * 1024); } while (0)
; #define PG8_MMA(ai, bj, At, Bt) do { __builtin_amdgcn_s_setprio(1); _Pragma("unroll") for (int m = 0; m < 4; ++m) _Pragma("unroll") for (int n = 0; n < 2; ++n) _Pragma("unroll") for (int k = 0; k < 2; ++k) \
;         acc[ai][bj][m][n] = __builtin_amdgcn_mfma_f32_16x16x32_bf16(Bt[n][k], At[m][k], acc[ai][bj][m][n], 0, 0, 0); __builtin_amdgcn_s_setprio(0); } while (0)
; #define PG8_WAIT_V(n) asm volatile("s_waitcnt vmcnt(" #n ")" ::: "memory")
; #define PG8_WAIT_L(n) asm volatile("s_waitcnt lgkmcnt(" #n ")" ::: "memory")
; #define PG8_BAR __builtin_amdgcn_s_barrier()
; #define PG8_SCHED __builtin_amdgcn_sched_barrier(0)
; template <class Epi>
; __device__ __forceinline__ void gemm_phase(LAS unsigned char* lds, const Gemm g, const StaticOrder& S, const Epi& E, const int tid) {
;     ...
;             PG8_LDA(At, 1, 1); PG8_STAGE(PG8_SB(1, 0), b3, voffB); PG8_STAGE(PG8_SB(1, 1), b3 + hstepB, voffB); PG8_STAGE(PG8_SA(1, 0), a3, voffA);
;             PG8_WAIT_V(8); PG8_WAIT_L(0); PG8_BAR; PG8_MMA(1, 0, At, B0); PG8_MMA(1, 1, At, B1); PG8_BAR; PG8_SCHED;
;         }
	s_add_i32 s16, s52, s20
	v_lshl_add_u64 v[164:165], v[164:165], 0, s[36:37]
	s_mov_b32 m0, s16
	ds_read_b128 v[202:205], v196 offset:49152
	ds_read_b128 v[206:209], v196 offset:50176
	ds_read_b128 v[210:213], v196 offset:51200
	ds_read_b128 v[214:217], v196 offset:52224
	ds_read_b128 v[226:229], v196 offset:53248
	ds_read_b128 v[230:233], v196 offset:54272
	ds_read_b128 v[234:237], v196 offset:55296
	ds_read_b128 v[238:241], v196 offset:56320
	global_load_lds_dwordx4 v[164:165], off
	s_add_i32 m0, s16, 0x2000
	s_add_u32 s16, s34, 0x40080
	v_lshl_add_u64 v[164:165], v[172:173], 0, s[36:37]
	s_addc_u32 s17, s35, 0
	s_add_i32 s34, s53, s20
	global_load_lds_dwordx4 v[164:165], off
	v_lshl_add_u64 v[164:165], s[16:17], 0, v[176:177]
	s_mov_b32 m0, s34
	s_nop 0
	global_load_lds_dwordx4 v[164:165], off
	v_lshl_add_u64 v[164:165], s[16:17], 0, v[144:145]
	s_add_i32 m0, s34, 0x2000
	s_nop 0
	global_load_lds_dwordx4 v[164:165], off
	v_lshl_add_u64 v[164:165], v[194:195], 0, s[76:77]
	s_mov_b32 m0, s42
	s_nop 0
	global_load_lds_dwordx4 v[164:165], off
	v_lshl_add_u64 v[164:165], v[198:199], 0, s[76:77]
	s_mov_b32 m0, s43
	s_nop 0
	global_load_lds_dwordx4 v[164:165], off
	s_waitcnt vmcnt(8)
	s_waitcnt lgkmcnt(0)
	s_barrier
	v_mfma_f32_16x16x32_bf16 v[60:63], v[128:131], v[202:205], v[60:63]
	v_mfma_f32_16x16x32_bf16 v[56:59], v[136:139], v[202:205], v[56:59]
	v_mfma_f32_16x16x32_bf16 v[52:55], v[128:131], v[210:213], v[52:55]
	v_mfma_f32_16x16x32_bf16 v[44:47], v[136:139], v[210:213], v[44:47]
	v_mfma_f32_16x16x32_bf16 v[36:39], v[128:131], v[226:229], v[36:39]
	v_mfma_f32_16x16x32_bf16 v[28:31], v[136:139], v[226:229], v[28:31]
	v_mfma_f32_16x16x32_bf16 v[20:23], v[128:131], v[234:237], v[20:23]
	v_mfma_f32_16x16x32_bf16 v[12:15], v[136:139], v[234:237], v[12:15]
	v_mfma_f32_16x16x32_bf16 v[60:63], v[132:135], v[206:209], v[60:63]
	v_mfma_f32_16x16x32_bf16 v[56:59], v[140:143], v[206:209], v[56:59]
	v_mfma_f32_16x16x32_bf16 v[52:55], v[132:135], v[214:217], v[52:55]
	v_mfma_f32_16x16x32_bf16 v[44:47], v[140:143], v[214:217], v[44:47]
	v_mfma_f32_16x16x32_bf16 v[36:39], v[132:135], v[230:233], v[36:39]
	v_mfma_f32_16x16x32_bf16 v[28:31], v[140:143], v[230:233], v[28:31]
	v_mfma_f32_16x16x32_bf16 v[20:23], v[132:135], v[238:241], v[20:23]
	v_mfma_f32_16x16x32_bf16 v[12:15], v[140:143], v[238:241], v[12:15]
	v_mfma_f32_16x16x32_bf16 v[48:51], v[156:159], v[202:205], v[48:51]
	v_mfma_f32_16x16x32_bf16 v[40:43], v[168:171], v[202:205], v[40:43]
	v_mfma_f32_16x16x32_bf16 v[32:35], v[156:159], v[210:213], v[32:35]
	v_mfma_f32_16x16x32_bf16 v[24:27], v[168:171], v[210:213], v[24:27]
	v_mfma_f32_16x16x32_bf16 v[16:19], v[156:159], v[226:229], v[16:19]
	v_mfma_f32_16x16x32_bf16 v[8:11], v[168:171], v[226:229], v[8:11]
	v_mfma_f32_16x16x32_bf16 v[4:7], v[156:159], v[234:237], v[4:7]
	v_mfma_f32_16x16x32_bf16 v[0:3], v[168:171], v[234:237], v[0:3]
	v_mfma_f32_16x16x32_bf16 v[48:51], v[160:163], v[206:209], v[48:51]
	v_mfma_f32_16x16x32_bf16 v[40:43], v[178:181], v[206:209], v[40:43]
	v_mfma_f32_16x16x32_bf16 v[32:35], v[160:163], v[214:217], v[32:35]
	v_mfma_f32_16x16x32_bf16 v[24:27], v[178:181], v[214:217], v[24:27]
	v_mfma_f32_16x16x32_bf16 v[16:19], v[160:163], v[230:233], v[16:19]
	v_mfma_f32_16x16x32_bf16 v[8:11], v[178:181], v[230:233], v[8:11]
	v_mfma_f32_16x16x32_bf16 v[4:7], v[160:163], v[238:241], v[4:7]
	v_mfma_f32_16x16x32_bf16 v[0:3], v[178:181], v[238:241], v[0:3]
	s_barrier
	s_add_i32 s51, s51, 2
	s_add_u32 s49, s49, 0x100
	s_addc_u32 s50, s50, 0
	s_cmp_gt_u32 s51, 13
	s_mov_b64 s[16:17], s[28:29]
	s_cbranch_scc0 .LBB0_225
	s_and_b64 vcc, exec, s[6:7]
	s_cbranch_vccz .LBB0_228
	s_barrier

; #define PG8_STAGE(bufoff, gbase, voff) do { _Pragma("unroll") for (int _i = 0; _i < 2; ++_i) \
;         __builtin_amdgcn_global_load_lds((const unsigned*)((const char*)(gbase) + (voff)[_i]), (LAS unsigned*)(lds + (bufoff) + ldsw + _i * 8192), 16, 0, 0); } while (0)
; #define PG8_LDA(dst, b, h) do { _Pragma("unroll") for (int m = 0; m < 4; ++m) _Pragma("unroll") for (int k = 0; k < 2; ++k) dst[m][k] = *(const LAS bf16x8*)(lds + PG8_SA(b, h) + aoff + m * 2048 + k * 1024); } while (0)
; #define PG8_LDB(dst, b, h) do { _Pragma("unroll") for (int n = 0; n < 2; ++n) _Pragma("unroll") for (int k = 0; k < 2; ++k) dst[n][k] = *(const LAS bf16x8*)(lds + PG8_SB(b, h) + boff + n * 2048 + k * 1024); } while (0)
; #define PG8_MMA(ai, bj, At, Bt) do { __builtin_amdgcn_s_setprio(1); _Pragma("unroll") for (int m = 0; m < 4; ++m) _Pragma("unroll") for (int n = 0; n < 2; ++n) _Pragma("unroll") for (int k = 0; k < 2; ++k) \
;         acc[ai][bj][m][n] = __builtin_amdgcn_mfma_f32_16x16x32_bf16(Bt[n][k], At[m][k], acc[ai][bj][m][n], 0, 0, 0); __builtin_amdgcn_s_setprio(0); } while (0)
; #define PG8_WAIT_V(n) asm volatile("s_waitcnt vmcnt(" #n ")" ::: "memory")
; #define PG8_WAIT_L(n) asm volatile("s_waitcnt lgkmcnt(" #n ")" ::: "memory")
; #define PG8_BAR __builtin_amdgcn_s_barrier()
; #define PG8_SCHED __builtin_amdgcn_sched_barrier(0)
; template <class Epi>
; __device__ __forceinline__ void gemm_phase(LAS unsigned char* lds, const Gemm g, const StaticOrder& S, const Epi& E, const int tid) {
;     ...
;         for (int t = 0; t < nt; t += 2) {
;             const bool last = (t == nt - 2);
;             const char* a1 = cA + (size_t)(t + 1) * kstepA;
;             const char* a2 = last ? nA : cA + (size_t)(t + 2) * kstepA; const char* b2 = last ? nB : cB + (size_t)(t + 2) * kstep;
;             const char* a3 = a2 + kstepA; const char* b3 = b2 + kstep;
;             PG8_LDB(B0, 0, 0); PG8_LDB(B1, 0, 1); PG8_SCHED; PG8_LDA(At, 0, 0); PG8_STAGE(PG8_SA(1, 1), a1 + hstepA, voffA);
;             PG8_WAIT_V(8); PG8_WAIT_L(0); PG8_BAR; PG8_MMA(0, 0, At, B0); PG8_MMA(0, 1, At, B1); PG8_BAR; PG8_SCHED;
;             PG8_LDA(At, 0, 1); PG8_STAGE(PG8_SB(0, 0), b2, voffB); PG8_STAGE(PG8_SB(0, 1), b2 + hstepB, voffB); PG8_STAGE(PG8_SA(0, 0), a2, voffA);
.LBB0_339:
	s_add_u32 s34, s28, 0x1000
	s_addc_u32 s35, s29, 0
	s_add_i32 s56, 0, 0x10000
	s_cmp_eq_u32 s55, 12
	s_cselect_b32 s43, s15, s35
	s_cselect_b32 s42, s51, s34
	v_add_u32_e32 v142, s56, v145
	s_cselect_b32 s41, s13, s54
	s_cselect_b32 s40, s52, s53
	s_add_i32 s57, 0, 0x14000
	ds_read_b128 v[158:161], v142
	ds_read_b128 v[162:165], v142 offset:1024
	ds_read_b128 v[166:169], v142 offset:2048
	ds_read_b128 v[170:173], v142 offset:3072
	v_add_u32_e32 v142, s57, v145
	ds_read_b128 v[194:197], v142
	ds_read_b128 v[202:205], v142 offset:1024
	ds_read_b128 v[206:209], v142 offset:2048
	ds_read_b128 v[210:213], v142 offset:3072
	v_lshl_add_u64 v[146:147], s[28:29], 0, v[138:139]
	s_add_i32 m0, s23, 0xc000
	ds_read_b128 v[214:217], v157
	ds_read_b128 v[226:229], v157 offset:1024
	ds_read_b128 v[230:233], v157 offset:2048
	ds_read_b128 v[234:237], v157 offset:3072
	ds_read_b128 v[238:241], v157 offset:4096
	ds_read_b128 v[242:245], v157 offset:5120
	ds_read_b128 v[246:249], v157 offset:6144
	ds_read_b128 v[178:181], v157 offset:7168
	global_load_lds_dwordx4 v[146:147], off
	v_lshl_add_u64 v[146:147], s[28:29], 0, v[140:141]
	s_add_i32 m0, s23, 0xe000
	s_nop 0
	global_load_lds_dwordx4 v[146:147], off
	s_waitcnt vmcnt(8)
	s_waitcnt lgkmcnt(0)
	s_barrier
	v_mfma_f32_16x16x32_bf16 v[124:127], v[158:161], v[214:217], v[124:127]
	v_mfma_f32_16x16x32_bf16 v[120:123], v[166:169], v[214:217], v[120:123]
	v_mfma_f32_16x16x32_bf16 v[116:119], v[158:161], v[230:233], v[116:119]
	v_mfma_f32_16x16x32_bf16 v[108:111], v[166:169], v[230:233], v[108:111]
	v_mfma_f32_16x16x32_bf16 v[100:103], v[158:161], v[238:241], v[100:103]
	v_mfma_f32_16x16x32_bf16 v[92:95], v[166:169], v[238:241], v[92:95]
	v_mfma_f32_16x16x32_bf16 v[84:87], v[158:161], v[246:249], v[84:87]
	v_mfma_f32_16x16x32_bf16 v[76:79], v[166:169], v[246:249], v[76:79]
	v_mfma_f32_16x16x32_bf16 v[124:127], v[162:165], v[226:229], v[124:127]
	v_mfma_f32_16x16x32_bf16 v[120:123], v[170:173], v[226:229], v[120:123]
	v_mfma_f32_16x16x32_bf16 v[116:119], v[162:165], v[234:237], v[116:119]
	v_mfma_f32_16x16x32_bf16 v[108:111], v[170:173], v[234:237], v[108:111]
	v_mfma_f32_16x16x32_bf16 v[100:103], v[162:165], v[242:245], v[100:103]
	v_mfma_f32_16x16x32_bf16 v[92:95], v[170:173], v[242:245], v[92:95]
	v_mfma_f32_16x16x32_bf16 v[84:87], v[162:165], v[178:181], v[84:87]
	v_mfma_f32_16x16x32_bf16 v[76:79], v[170:173], v[178:181], v[76:79]
	v_mfma_f32_16x16x32_bf16 v[112:115], v[194:197], v[214:217], v[112:115]
	v_mfma_f32_16x16x32_bf16 v[104:107], v[206:209], v[214:217], v[104:107]
	v_mfma_f32_16x16x32_bf16 v[96:99], v[194:197], v[230:233], v[96:99]
	v_mfma_f32_16x16x32_bf16 v[88:91], v[206:209], v[230:233], v[88:91]
	v_mfma_f32_16x16x32_bf16 v[80:83], v[194:197], v[238:241], v[80:83]
	v_mfma_f32_16x16x32_bf16 v[72:75], v[206:209], v[238:241], v[72:75]
	v_mfma_f32_16x16x32_bf16 v[68:71], v[194:197], v[246:249], v[68:71]
	v_mfma_f32_16x16x32_bf16 v[64:67], v[206:209], v[246:249], v[64:67]
	v_mfma_f32_16x16x32_bf16 v[112:115], v[202:205], v[226:229], v[112:115]
	v_mfma_f32_16x16x32_bf16 v[104:107], v[210:213], v[226:229], v[104:107]
	v_mfma_f32_16x16x32_bf16 v[96:99], v[202:205], v[234:237], v[96:99]
	v_mfma_f32_16x16x32_bf16 v[88:91], v[210:213], v[234:237], v[88:91]
	v_mfma_f32_16x16x32_bf16 v[80:83], v[202:205], v[242:245], v[80:83]
	v_mfma_f32_16x16x32_bf16 v[72:75], v[210:213], v[242:245], v[72:75]
	v_mfma_f32_16x16x32_bf16 v[68:71], v[202:205], v[178:181], v[68:71]
	v_mfma_f32_16x16x32_bf16 v[64:67], v[210:213], v[178:181], v[64:67]
	s_barrier
	s_add_i32 s28, s56, s22
	v_lshl_add_u64 v[146:147], s[40:41], 0, v[132:133]
	s_mov_b32 m0, s28
	ds_read_b128 v[178:181], v157 offset:16384
	ds_read_b128 v[214:217], v157 offset:17408
	ds_read_b128 v[226:229], v157 offset:18432
	ds_read_b128 v[230:233], v157 offset:19456
	ds_read_b128 v[234:237], v157 offset:20480
	ds_read_b128 v[238:241], v157 offset:21504
	ds_read_b128 v[242:245], v157 offset:22528
	ds_read_b128 v[246:249], v157 offset:23552
	global_load_lds_dwordx4 v[146:147], off
	s_add_i32 m0, s28, 0x2000
	s_add_u32 s28, s40, 0x40000
	v_lshl_add_u64 v[150:151], s[40:41], 0, v[128:129]
	s_addc_u32 s29, s41, 0
	s_add_i32 s56, s57, s22
	global_load_lds_dwordx4 v[150:151], off
	v_lshl_add_u64 v[154:155], s[28:29], 0, v[132:133]
	s_mov_b32 m0, s56
	v_lshl_add_u64 v[174:175], s[42:43], 0, v[130:131]
	global_load_lds_dwordx4 v[154:155], off
	v_lshl_add_u64 v[154:155], s[28:29], 0, v[128:129]
	s_add_i32 m0, s56, 0x2000
	s_nop 0
	global_load_lds_dwordx4 v[154:155], off
	v_lshl_add_u64 v[154:155], s[42:43], 0, v[134:135]
	s_mov_b32 m0, s23
	s_nop 0
	global_load_lds_dwordx4 v[154:155], off
	s_mov_b32 m0, s30
	s_nop 0
	global_load_lds_dwordx4 v[174:175], off
	s_waitcnt vmcnt(8)
	s_waitcnt lgkmcnt(0)
	s_barrier
; #define PG8_STAGE(bufoff, gbase, voff) do { _Pragma("unroll") for (int _i = 0; _i < 2; ++_i) \
;         __builtin_amdgcn_global_load_lds((const unsigned*)((const char*)(gbase) + (voff)[_i]), (LAS unsigned*)(lds + (bufoff) + ldsw + _i * 8192), 16, 0, 0); } while (0)
; #define PG8_LDA(dst, b, h) do { _Pragma("unroll") for (int m = 0; m < 4; ++m) _Pragma("unroll") for (int k = 0; k < 2; ++k) dst[m][k] = *(const LAS bf16x8*)(lds + PG8_SA(b, h) + aoff + m * 2048 + k * 1024); } while (0)
; #define PG8_LDB(dst, b, h) do { _Pragma("unroll") for (int n = 0; n < 2; ++n) _Pragma("unroll") for (int k = 0; k < 2; ++k) dst[n][k] = *(const LAS bf16x8*)(lds + PG8_SB(b, h) + boff + n * 2048 + k * 1024); } while (0)
; #define PG8_MMA(ai, bj, At, Bt) do { __builtin_amdgcn_s_setprio(1); _Pragma("unroll") for (int m = 0; m < 4; ++m) _Pragma("unroll") for (int n = 0; n < 2; ++n) _Pragma("unroll") for (int k = 0; k < 2; ++k) \
;         acc[ai][bj][m][n] = __builtin_amdgcn_mfma_f32_16x16x32_bf16(Bt[n][k], At[m][k], acc[ai][bj][m][n], 0, 0, 0); __builtin_amdgcn_s_setprio(0); } while (0)
; #define PG8_WAIT_V(n) asm volatile("s_waitcnt vmcnt(" #n ")" ::: "memory")
; #define PG8_WAIT_L(n) asm volatile("s_waitcnt lgkmcnt(" #n ")" ::: "memory")
; #define PG8_BAR __builtin_amdgcn_s_barrier()
; #define PG8_SCHED __builtin_amdgcn_sched_barrier(0)
; template <class Epi>
; __device__ __forceinline__ void gemm_phase(LAS unsigned char* lds, const Gemm g, const StaticOrder& S, const Epi& E, const int tid) {
;     ...
;             PG8_WAIT_V(8); PG8_WAIT_L(0); PG8_BAR; PG8_MMA(1, 0, At, B0); PG8_MMA(1, 1, At, B1); PG8_BAR; PG8_SCHED;
;             PG8_LDB(B0, 1, 0); PG8_LDB(B1, 1, 1); PG8_SCHED; PG8_LDA(At, 1, 0); PG8_STAGE(PG8_SA(0, 1), a2 + hstepA, voffA);
;             PG8_WAIT_V(8); PG8_WAIT_L(0); PG8_BAR; PG8_MMA(0, 0, At, B0); PG8_MMA(0, 1, At, B1); PG8_BAR; PG8_SCHED;
	v_mfma_f32_16x16x32_bf16 v[60:63], v[158:161], v[178:181], v[60:63]
	v_mfma_f32_16x16x32_bf16 v[56:59], v[166:169], v[178:181], v[56:59]
	v_mfma_f32_16x16x32_bf16 v[52:55], v[158:161], v[226:229], v[52:55]
	v_mfma_f32_16x16x32_bf16 v[44:47], v[166:169], v[226:229], v[44:47]
	v_mfma_f32_16x16x32_bf16 v[36:39], v[158:161], v[234:237], v[36:39]
	v_mfma_f32_16x16x32_bf16 v[28:31], v[166:169], v[234:237], v[28:31]
	v_mfma_f32_16x16x32_bf16 v[20:23], v[158:161], v[242:245], v[20:23]
	v_mfma_f32_16x16x32_bf16 v[12:15], v[166:169], v[242:245], v[12:15]
	v_mfma_f32_16x16x32_bf16 v[60:63], v[162:165], v[214:217], v[60:63]
	v_mfma_f32_16x16x32_bf16 v[56:59], v[170:173], v[214:217], v[56:59]
	v_mfma_f32_16x16x32_bf16 v[52:55], v[162:165], v[230:233], v[52:55]
	v_mfma_f32_16x16x32_bf16 v[44:47], v[170:173], v[230:233], v[44:47]
	v_mfma_f32_16x16x32_bf16 v[36:39], v[162:165], v[238:241], v[36:39]
	v_mfma_f32_16x16x32_bf16 v[28:31], v[170:173], v[238:241], v[28:31]
	v_mfma_f32_16x16x32_bf16 v[20:23], v[162:165], v[246:249], v[20:23]
	v_mfma_f32_16x16x32_bf16 v[12:15], v[170:173], v[246:249], v[12:15]
	v_mfma_f32_16x16x32_bf16 v[48:51], v[194:197], v[178:181], v[48:51]
	v_mfma_f32_16x16x32_bf16 v[40:43], v[206:209], v[178:181], v[40:43]
	v_mfma_f32_16x16x32_bf16 v[32:35], v[194:197], v[226:229], v[32:35]
	v_mfma_f32_16x16x32_bf16 v[24:27], v[206:209], v[226:229], v[24:27]
	v_mfma_f32_16x16x32_bf16 v[16:19], v[194:197], v[234:237], v[16:19]
	v_mfma_f32_16x16x32_bf16 v[8:11], v[206:209], v[234:237], v[8:11]
	v_mfma_f32_16x16x32_bf16 v[4:7], v[194:197], v[242:245], v[4:7]
	v_mfma_f32_16x16x32_bf16 v[0:3], v[206:209], v[242:245], v[0:3]
	v_mfma_f32_16x16x32_bf16 v[48:51], v[202:205], v[214:217], v[48:51]
	v_mfma_f32_16x16x32_bf16 v[40:43], v[210:213], v[214:217], v[40:43]
	v_mfma_f32_16x16x32_bf16 v[32:35], v[202:205], v[230:233], v[32:35]
	v_mfma_f32_16x16x32_bf16 v[24:27], v[210:213], v[230:233], v[24:27]
	v_mfma_f32_16x16x32_bf16 v[16:19], v[202:205], v[238:241], v[16:19]
	v_mfma_f32_16x16x32_bf16 v[8:11], v[210:213], v[238:241], v[8:11]
	v_mfma_f32_16x16x32_bf16 v[4:7], v[202:205], v[246:249], v[4:7]
	v_mfma_f32_16x16x32_bf16 v[0:3], v[210:213], v[246:249], v[0:3]
	s_barrier
	s_add_i32 s56, 0, 0x18000
	v_add_u32_e32 v142, s56, v145
	s_add_i32 s57, 0, 0x1c000
	ds_read_b128 v[158:161], v142
	ds_read_b128 v[162:165], v142 offset:1024
	ds_read_b128 v[166:169], v142 offset:2048
	ds_read_b128 v[170:173], v142 offset:3072
	v_add_u32_e32 v142, s57, v145
	ds_read_b128 v[178:181], v142
	ds_read_b128 v[194:197], v142 offset:1024
	ds_read_b128 v[202:205], v142 offset:2048
	ds_read_b128 v[206:209], v142 offset:3072
	s_add_u32 s28, s42, 0x40000
	s_addc_u32 s29, s43, 0
	s_mov_b32 m0, s44
	v_lshl_add_u64 v[198:199], s[28:29], 0, v[134:135]
	ds_read_b128 v[210:213], v157 offset:32768
	ds_read_b128 v[214:217], v157 offset:33792
	ds_read_b128 v[226:229], v157 offset:34816
	ds_read_b128 v[230:233], v157 offset:35840
	ds_read_b128 v[234:237], v157 offset:36864
	ds_read_b128 v[238:241], v157 offset:37888
	ds_read_b128 v[242:245], v157 offset:38912
	ds_read_b128 v[246:249], v157 offset:39936
	global_load_lds_dwordx4 v[198:199], off
	v_lshl_add_u64 v[198:199], s[28:29], 0, v[130:131]
	s_mov_b32 m0, s45
	s_nop 0
	global_load_lds_dwordx4 v[198:199], off
	s_waitcnt vmcnt(8)
	s_waitcnt lgkmcnt(0)
	s_barrier
	v_mfma_f32_16x16x32_bf16 v[124:127], v[158:161], v[210:213], v[124:127]
	v_mfma_f32_16x16x32_bf16 v[120:123], v[166:169], v[210:213], v[120:123]
	v_mfma_f32_16x16x32_bf16 v[116:119], v[158:161], v[226:229], v[116:119]
	v_mfma_f32_16x16x32_bf16 v[108:111], v[166:169], v[226:229], v[108:111]
	v_mfma_f32_16x16x32_bf16 v[100:103], v[158:161], v[234:237], v[100:103]
	v_mfma_f32_16x16x32_bf16 v[92:95], v[166:169], v[234:237], v[92:95]
	v_mfma_f32_16x16x32_bf16 v[84:87], v[158:161], v[242:245], v[84:87]
	v_mfma_f32_16x16x32_bf16 v[76:79], v[166:169], v[242:245], v[76:79]
	v_mfma_f32_16x16x32_bf16 v[124:127], v[162:165], v[214:217], v[124:127]
	v_mfma_f32_16x16x32_bf16 v[120:123], v[170:173], v[214:217], v[120:123]
	v_mfma_f32_16x16x32_bf16 v[116:119], v[162:165], v[230:233], v[116:119]
	v_mfma_f32_16x16x32_bf16 v[108:111], v[170:173], v[230:233], v[108:111]
	v_mfma_f32_16x16x32_bf16 v[100:103], v[162:165], v[238:241], v[100:103]
	v_mfma_f32_16x16x32_bf16 v[92:95], v[170:173], v[238:241], v[92:95]
	v_mfma_f32_16x16x32_bf16 v[84:87], v[162:165], v[246:249], v[84:87]
	v_mfma_f32_16x16x32_bf16 v[76:79], v[170:173], v[246:249], v[76:79]
	v_mfma_f32_16x16x32_bf16 v[112:115], v[178:181], v[210:213], v[112:115]
	v_mfma_f32_16x16x32_bf16 v[104:107], v[202:205], v[210:213], v[104:107]
	v_mfma_f32_16x16x32_bf16 v[96:99], v[178:181], v[226:229], v[96:99]
	v_mfma_f32_16x16x32_bf16 v[88:91], v[202:205], v[226:229], v[88:91]
	v_mfma_f32_16x16x32_bf16 v[80:83], v[178:181], v[234:237], v[80:83]
	v_mfma_f32_16x16x32_bf16 v[72:75], v[202:205], v[234:237], v[72:75]
	v_mfma_f32_16x16x32_bf16 v[68:71], v[178:181], v[242:245], v[68:71]
	v_mfma_f32_16x16x32_bf16 v[64:67], v[202:205], v[242:245], v[64:67]
	v_mfma_f32_16x16x32_bf16 v[112:115], v[194:197], v[214:217], v[112:115]
	v_mfma_f32_16x16x32_bf16 v[104:107], v[206:209], v[214:217], v[104:107]
	v_mfma_f32_16x16x32_bf16 v[96:99], v[194:197], v[230:233], v[96:99]
	v_mfma_f32_16x16x32_bf16 v[88:91], v[206:209], v[230:233], v[88:91]
	v_mfma_f32_16x16x32_bf16 v[80:83], v[194:197], v[238:241], v[80:83]
	v_mfma_f32_16x16x32_bf16 v[72:75], v[206:209], v[238:241], v[72:75]
	v_mfma_f32_16x16x32_bf16 v[68:71], v[194:197], v[246:249], v[68:71]
	v_mfma_f32_16x16x32_bf16 v[64:67], v[206:209], v[246:249], v[64:67]
	s_barrier
; #define PG8_STAGE(bufoff, gbase, voff) do { _Pragma("unroll") for (int _i = 0; _i < 2; ++_i) \
;         __builtin_amdgcn_global_load_lds((const unsigned*)((const char*)(gbase) + (voff)[_i]), (LAS unsigned*)(lds + (bufoff) + ldsw + _i * 8192), 16, 0, 0); } while (0)
; #define PG8_LDA(dst, b, h) do { _Pragma("unroll") for (int m = 0; m < 4; ++m) _Pragma("unroll") for (int k = 0; k < 2; ++k) dst[m][k] = *(const LAS bf16x8*)(lds + PG8_SA(b, h) + aoff + m * 2048 + k * 1024); } while (0)
; #define PG8_MMA(ai, bj, At, Bt) do { __builtin_amdgcn_s_setprio(1); _Pragma("unroll") for (int m = 0; m < 4; ++m) _Pragma("unroll") for (int n = 0; n < 2; ++n) _Pragma("unroll") for (int k = 0; k < 2; ++k) \
;         acc[ai][bj][m][n] = __builtin_amdgcn_mfma_f32_16x16x32_bf16(Bt[n][k], At[m][k], acc[ai][bj][m][n], 0, 0, 0); __builtin_amdgcn_s_setprio(0); } while (0)
; #define PG8_WAIT_V(n) asm volatile("s_waitcnt vmcnt(" #n ")" ::: "memory")
; #define PG8_WAIT_L(n) asm volatile("s_waitcnt lgkmcnt(" #n ")" ::: "memory")
; #define PG8_BAR __builtin_amdgcn_s_barrier()
; #define PG8_SCHED __builtin_amdgcn_sched_barrier(0)
; template <class Epi>
; __device__ __forceinline__ void gemm_phase(LAS unsigned char* lds, const Gemm g, const StaticOrder& S, const Epi& E, const int tid) {
;     ...
;             PG8_LDA(At, 1, 1); PG8_STAGE(PG8_SB(1, 0), b3, voffB); PG8_STAGE(PG8_SB(1, 1), b3 + hstepB, voffB); PG8_STAGE(PG8_SA(1, 0), a3, voffA);
;             PG8_WAIT_V(8); PG8_WAIT_L(0); PG8_BAR; PG8_MMA(1, 0, At, B0); PG8_MMA(1, 1, At, B1); PG8_BAR; PG8_SCHED;
;         }
	s_add_i32 s28, s56, s22
	v_lshl_add_u64 v[146:147], v[146:147], 0, s[36:37]
	s_mov_b32 m0, s28
	ds_read_b128 v[210:213], v157 offset:49152
	ds_read_b128 v[214:217], v157 offset:50176
	ds_read_b128 v[226:229], v157 offset:51200
	ds_read_b128 v[230:233], v157 offset:52224
	ds_read_b128 v[234:237], v157 offset:53248
	ds_read_b128 v[238:241], v157 offset:54272
	ds_read_b128 v[242:245], v157 offset:55296
	ds_read_b128 v[246:249], v157 offset:56320
	global_load_lds_dwordx4 v[146:147], off
	s_add_i32 m0, s28, 0x2000
	s_add_u32 s28, s40, 0x40080
	v_lshl_add_u64 v[146:147], v[150:151], 0, s[36:37]
	s_addc_u32 s29, s41, 0
	s_add_i32 s40, s57, s22
	global_load_lds_dwordx4 v[146:147], off
	v_lshl_add_u64 v[146:147], s[28:29], 0, v[132:133]
	s_mov_b32 m0, s40
	s_nop 0
	global_load_lds_dwordx4 v[146:147], off
	v_lshl_add_u64 v[146:147], s[28:29], 0, v[128:129]
	s_add_i32 m0, s40, 0x2000
	s_nop 0
	global_load_lds_dwordx4 v[146:147], off
	v_lshl_add_u64 v[146:147], v[154:155], 0, s[76:77]
	s_mov_b32 m0, s46
	s_nop 0
	global_load_lds_dwordx4 v[146:147], off
	v_lshl_add_u64 v[146:147], v[174:175], 0, s[76:77]
	s_mov_b32 m0, s47
	s_nop 0
	global_load_lds_dwordx4 v[146:147], off
	s_waitcnt vmcnt(8)
	s_waitcnt lgkmcnt(0)
	s_barrier
	v_mfma_f32_16x16x32_bf16 v[60:63], v[158:161], v[210:213], v[60:63]
	v_mfma_f32_16x16x32_bf16 v[56:59], v[166:169], v[210:213], v[56:59]
	v_mfma_f32_16x16x32_bf16 v[52:55], v[158:161], v[226:229], v[52:55]
	v_mfma_f32_16x16x32_bf16 v[44:47], v[166:169], v[226:229], v[44:47]
	v_mfma_f32_16x16x32_bf16 v[36:39], v[158:161], v[234:237], v[36:39]
	v_mfma_f32_16x16x32_bf16 v[28:31], v[166:169], v[234:237], v[28:31]
	v_mfma_f32_16x16x32_bf16 v[20:23], v[158:161], v[242:245], v[20:23]
	v_mfma_f32_16x16x32_bf16 v[12:15], v[166:169], v[242:245], v[12:15]
	v_mfma_f32_16x16x32_bf16 v[60:63], v[162:165], v[214:217], v[60:63]
	v_mfma_f32_16x16x32_bf16 v[56:59], v[170:173], v[214:217], v[56:59]
	v_mfma_f32_16x16x32_bf16 v[52:55], v[162:165], v[230:233], v[52:55]
	v_mfma_f32_16x16x32_bf16 v[44:47], v[170:173], v[230:233], v[44:47]
	v_mfma_f32_16x16x32_bf16 v[36:39], v[162:165], v[238:241], v[36:39]
	v_mfma_f32_16x16x32_bf16 v[28:31], v[170:173], v[238:241], v[28:31]
	v_mfma_f32_16x16x32_bf16 v[20:23], v[162:165], v[246:249], v[20:23]
	v_mfma_f32_16x16x32_bf16 v[12:15], v[170:173], v[246:249], v[12:15]
	v_mfma_f32_16x16x32_bf16 v[48:51], v[178:181], v[210:213], v[48:51]
	v_mfma_f32_16x16x32_bf16 v[40:43], v[202:205], v[210:213], v[40:43]
	v_mfma_f32_16x16x32_bf16 v[32:35], v[178:181], v[226:229], v[32:35]
	v_mfma_f32_16x16x32_bf16 v[24:27], v[202:205], v[226:229], v[24:27]
	v_mfma_f32_16x16x32_bf16 v[16:19], v[178:181], v[234:237], v[16:19]
	v_mfma_f32_16x16x32_bf16 v[8:11], v[202:205], v[234:237], v[8:11]
	v_mfma_f32_16x16x32_bf16 v[4:7], v[178:181], v[242:245], v[4:7]
	v_mfma_f32_16x16x32_bf16 v[0:3], v[202:205], v[242:245], v[0:3]
	v_mfma_f32_16x16x32_bf16 v[48:51], v[194:197], v[214:217], v[48:51]
	v_mfma_f32_16x16x32_bf16 v[40:43], v[206:209], v[214:217], v[40:43]
	v_mfma_f32_16x16x32_bf16 v[32:35], v[194:197], v[230:233], v[32:35]
	v_mfma_f32_16x16x32_bf16 v[24:27], v[206:209], v[230:233], v[24:27]
	v_mfma_f32_16x16x32_bf16 v[16:19], v[194:197], v[238:241], v[16:19]
	v_mfma_f32_16x16x32_bf16 v[8:11], v[206:209], v[238:241], v[8:11]
	v_mfma_f32_16x16x32_bf16 v[4:7], v[194:197], v[246:249], v[4:7]
	v_mfma_f32_16x16x32_bf16 v[0:3], v[206:209], v[246:249], v[0:3]
	s_barrier
	s_add_i32 s55, s55, 2
	s_add_u32 s53, s53, 0x100
	s_addc_u32 s54, s54, 0
	s_cmp_gt_u32 s55, 13
	s_mov_b64 s[28:29], s[34:35]
	s_cbranch_scc0 .LBB0_339
	s_and_b64 vcc, exec, s[10:11]
	s_cbranch_vccz .LBB0_342
	s_barrier

; #define PG8_STAGE(bufoff, gbase, voff) do { _Pragma("unroll") for (int _i = 0; _i < 2; ++_i) \
;         __builtin_amdgcn_global_load_lds((const unsigned*)((const char*)(gbase) + (voff)[_i]), (LAS unsigned*)(lds + (bufoff) + ldsw + _i * 8192), 16, 0, 0); } while (0)
; #define PG8_LDA(dst, b, h) do { _Pragma("unroll") for (int m = 0; m < 4; ++m) _Pragma("unroll") for (int k = 0; k < 2; ++k) dst[m][k] = *(const LAS bf16x8*)(lds + PG8_SA(b, h) + aoff + m * 2048 + k * 1024); } while (0)
; #define PG8_LDB(dst, b, h) do { _Pragma("unroll") for (int n = 0; n < 2; ++n) _Pragma("unroll") for (int k = 0; k < 2; ++k) dst[n][k] = *(const LAS bf16x8*)(lds + PG8_SB(b, h) + boff + n * 2048 + k * 1024); } while (0)
; #define PG8_MMA(ai, bj, At, Bt) do { __builtin_amdgcn_s_setprio(1); _Pragma("unroll") for (int m = 0; m < 4; ++m) _Pragma("unroll") for (int n = 0; n < 2; ++n) _Pragma("unroll") for (int k = 0; k < 2; ++k) \
;         acc[ai][bj][m][n] = __builtin_amdgcn_mfma_f32_16x16x32_bf16(Bt[n][k], At[m][k], acc[ai][bj][m][n], 0, 0, 0); __builtin_amdgcn_s_setprio(0); } while (0)
; #define PG8_WAIT_V(n) asm volatile("s_waitcnt vmcnt(" #n ")" ::: "memory")
; #define PG8_WAIT_L(n) asm volatile("s_waitcnt lgkmcnt(" #n ")" ::: "memory")
; #define PG8_BAR __builtin_amdgcn_s_barrier()
; #define PG8_SCHED __builtin_amdgcn_sched_barrier(0)
; template <class Epi>
; __device__ __forceinline__ void gemm_phase(LAS unsigned char* lds, const Gemm g, const StaticOrder& S, const Epi& E, const int tid) {
;     ...
;         for (int t = 0; t < nt; t += 2) {
;             const bool last = (t == nt - 2);
;             const char* a1 = cA + (size_t)(t + 1) * kstepA;
;             const char* a2 = last ? nA : cA + (size_t)(t + 2) * kstepA; const char* b2 = last ? nB : cB + (size_t)(t + 2) * kstep;
;             const char* a3 = a2 + kstepA; const char* b3 = b2 + kstep;
;             PG8_LDB(B0, 0, 0); PG8_LDB(B1, 0, 1); PG8_SCHED; PG8_LDA(At, 0, 0); PG8_STAGE(PG8_SA(1, 1), a1 + hstepA, voffA);
;             PG8_WAIT_V(8); PG8_WAIT_L(0); PG8_BAR; PG8_MMA(0, 0, At, B0); PG8_MMA(0, 1, At, B1); PG8_BAR; PG8_SCHED;
;             PG8_LDA(At, 0, 1); PG8_STAGE(PG8_SB(0, 0), b2, voffB); PG8_STAGE(PG8_SB(0, 1), b2 + hstepB, voffB); PG8_STAGE(PG8_SA(0, 0), a2, voffA);
.LBB0_393:
	s_add_u32 s80, s28, 1
	s_addc_u32 s81, s29, 0
	s_add_u32 s34, s28, 2
	s_addc_u32 s35, s29, 0
	s_lshl_b64 s[52:53], s[34:35], s61
	s_add_u32 s29, s2, s52
	s_addc_u32 s52, s3, s53
	s_cmp_eq_u32 s65, s28
	s_cselect_b32 s53, s9, s52
	s_cselect_b32 s52, s8, s29
	s_cselect_b32 s82, s50, s73
	s_cselect_b32 s83, s51, s75
	s_add_u32 s28, s52, s40
	s_addc_u32 s29, s53, s41
	s_add_i32 s84, 0, 0x10000
	s_add_i32 s85, 0, 0x14000
	v_add_u32_e32 v140, s84, v225
	v_add_u32_e32 v156, s85, v225
	ds_read_b128 v[124:127], v140
	ds_read_b128 v[128:131], v140 offset:1024
	ds_read_b128 v[136:139], v140 offset:2048
	ds_read_b128 v[140:143], v140 offset:3072
	ds_read_b128 v[144:147], v156
	ds_read_b128 v[148:151], v156 offset:1024
	ds_read_b128 v[152:155], v156 offset:2048
	ds_read_b128 v[156:159], v156 offset:3072
	s_lshl_b64 s[80:81], s[80:81], s61
	s_add_u32 s80, s71, s80
	s_addc_u32 s81, s72, s81
	v_lshl_add_u64 v[178:179], s[80:81], 0, v[194:195]
	s_add_i32 m0, s23, 0xc000
	ds_read_b128 v[160:163], v226
	ds_read_b128 v[164:167], v226 offset:1024
	ds_read_b128 v[168:171], v226 offset:2048
	ds_read_b128 v[172:175], v226 offset:3072
	ds_read_b128 v[202:205], v226 offset:4096
	ds_read_b128 v[206:209], v226 offset:5120
	ds_read_b128 v[210:213], v226 offset:6144
	ds_read_b128 v[214:217], v226 offset:7168
	global_load_lds_dwordx4 v[178:179], off
	v_lshl_add_u64 v[178:179], s[80:81], 0, v[198:199]
	s_add_i32 m0, s23, 0xe000
	s_nop 0
	global_load_lds_dwordx4 v[178:179], off
	s_waitcnt vmcnt(8)
	s_waitcnt lgkmcnt(0)
	s_barrier
	v_mfma_f32_16x16x32_bf16 v[132:135], v[124:127], v[160:163], v[132:135]
	v_mfma_f32_16x16x32_bf16 v[120:123], v[136:139], v[160:163], v[120:123]
	v_mfma_f32_16x16x32_bf16 v[108:111], v[124:127], v[168:171], v[108:111]
	v_mfma_f32_16x16x32_bf16 v[104:107], v[136:139], v[168:171], v[104:107]
	v_mfma_f32_16x16x32_bf16 v[92:95], v[124:127], v[202:205], v[92:95]
	v_mfma_f32_16x16x32_bf16 v[88:91], v[136:139], v[202:205], v[88:91]
	v_mfma_f32_16x16x32_bf16 v[76:79], v[124:127], v[210:213], v[76:79]
	v_mfma_f32_16x16x32_bf16 v[72:75], v[136:139], v[210:213], v[72:75]
	v_mfma_f32_16x16x32_bf16 v[132:135], v[128:131], v[164:167], v[132:135]
	v_mfma_f32_16x16x32_bf16 v[120:123], v[140:143], v[164:167], v[120:123]
	v_mfma_f32_16x16x32_bf16 v[108:111], v[128:131], v[172:175], v[108:111]
	v_mfma_f32_16x16x32_bf16 v[104:107], v[140:143], v[172:175], v[104:107]
	v_mfma_f32_16x16x32_bf16 v[92:95], v[128:131], v[206:209], v[92:95]
	v_mfma_f32_16x16x32_bf16 v[88:91], v[140:143], v[206:209], v[88:91]
	v_mfma_f32_16x16x32_bf16 v[76:79], v[128:131], v[214:217], v[76:79]
	v_mfma_f32_16x16x32_bf16 v[72:75], v[140:143], v[214:217], v[72:75]
	v_mfma_f32_16x16x32_bf16 v[116:119], v[144:147], v[160:163], v[116:119]
	v_mfma_f32_16x16x32_bf16 v[112:115], v[152:155], v[160:163], v[112:115]
	v_mfma_f32_16x16x32_bf16 v[100:103], v[144:147], v[168:171], v[100:103]
	v_mfma_f32_16x16x32_bf16 v[96:99], v[152:155], v[168:171], v[96:99]
	v_mfma_f32_16x16x32_bf16 v[84:87], v[144:147], v[202:205], v[84:87]
	v_mfma_f32_16x16x32_bf16 v[80:83], v[152:155], v[202:205], v[80:83]
	v_mfma_f32_16x16x32_bf16 v[68:71], v[144:147], v[210:213], v[68:71]
	v_mfma_f32_16x16x32_bf16 v[64:67], v[152:155], v[210:213], v[64:67]
	v_mfma_f32_16x16x32_bf16 v[116:119], v[148:151], v[164:167], v[116:119]
	v_mfma_f32_16x16x32_bf16 v[112:115], v[156:159], v[164:167], v[112:115]
	v_mfma_f32_16x16x32_bf16 v[100:103], v[148:151], v[172:175], v[100:103]
	v_mfma_f32_16x16x32_bf16 v[96:99], v[156:159], v[172:175], v[96:99]
	v_mfma_f32_16x16x32_bf16 v[84:87], v[148:151], v[206:209], v[84:87]
	v_mfma_f32_16x16x32_bf16 v[80:83], v[156:159], v[206:209], v[80:83]
	v_mfma_f32_16x16x32_bf16 v[68:71], v[148:151], v[214:217], v[68:71]
	v_mfma_f32_16x16x32_bf16 v[64:67], v[156:159], v[214:217], v[64:67]
	s_barrier
	s_add_i32 s80, s84, s17
	v_lshl_add_u64 v[178:179], s[82:83], 0, v[176:177]
	s_mov_b32 m0, s80
	ds_read_b128 v[160:163], v226 offset:16384
	ds_read_b128 v[164:167], v226 offset:17408
	ds_read_b128 v[168:171], v226 offset:18432
	ds_read_b128 v[172:175], v226 offset:19456
	ds_read_b128 v[202:205], v226 offset:20480
	ds_read_b128 v[206:209], v226 offset:21504
	ds_read_b128 v[210:213], v226 offset:22528
	ds_read_b128 v[214:217], v226 offset:23552
	global_load_lds_dwordx4 v[178:179], off
	s_add_i32 m0, s80, 0x2000
	s_add_u32 s80, s82, s42
	v_lshl_add_u64 v[180:181], s[82:83], 0, v[196:197]
	s_addc_u32 s81, s83, s43
	s_add_i32 s82, s85, s17
	global_load_lds_dwordx4 v[180:181], off
	v_lshl_add_u64 v[218:219], s[80:81], 0, v[176:177]
	s_mov_b32 m0, s82
	v_lshl_add_u64 v[228:229], s[80:81], 0, v[196:197]
	global_load_lds_dwordx4 v[218:219], off
	s_add_i32 m0, s82, 0x2000
	v_lshl_add_u64 v[230:231], s[52:53], 0, v[194:195]
	global_load_lds_dwordx4 v[228:229], off
	s_mov_b32 m0, s23
	s_nop 0
	global_load_lds_dwordx4 v[230:231], off
	v_lshl_add_u64 v[230:231], s[52:53], 0, v[198:199]
	s_mov_b32 m0, s54
	s_nop 0
	global_load_lds_dwordx4 v[230:231], off
	s_waitcnt vmcnt(8)
	s_waitcnt lgkmcnt(0)
	s_barrier
; #define PG8_STAGE(bufoff, gbase, voff) do { _Pragma("unroll") for (int _i = 0; _i < 2; ++_i) \
;         __builtin_amdgcn_global_load_lds((const unsigned*)((const char*)(gbase) + (voff)[_i]), (LAS unsigned*)(lds + (bufoff) + ldsw + _i * 8192), 16, 0, 0); } while (0)
; #define PG8_LDA(dst, b, h) do { _Pragma("unroll") for (int m = 0; m < 4; ++m) _Pragma("unroll") for (int k = 0; k < 2; ++k) dst[m][k] = *(const LAS bf16x8*)(lds + PG8_SA(b, h) + aoff + m * 2048 + k * 1024); } while (0)
; #define PG8_LDB(dst, b, h) do { _Pragma("unroll") for (int n = 0; n < 2; ++n) _Pragma("unroll") for (int k = 0; k < 2; ++k) dst[n][k] = *(const LAS bf16x8*)(lds + PG8_SB(b, h) + boff + n * 2048 + k * 1024); } while (0)
; #define PG8_MMA(ai, bj, At, Bt) do { __builtin_amdgcn_s_setprio(1); _Pragma("unroll") for (int m = 0; m < 4; ++m) _Pragma("unroll") for (int n = 0; n < 2; ++n) _Pragma("unroll") for (int k = 0; k < 2; ++k) \
;         acc[ai][bj][m][n] = __builtin_amdgcn_mfma_f32_16x16x32_bf16(Bt[n][k], At[m][k], acc[ai][bj][m][n], 0, 0, 0); __builtin_amdgcn_s_setprio(0); } while (0)
; #define PG8_WAIT_V(n) asm volatile("s_waitcnt vmcnt(" #n ")" ::: "memory")
; #define PG8_WAIT_L(n) asm volatile("s_waitcnt lgkmcnt(" #n ")" ::: "memory")
; #define PG8_BAR __builtin_amdgcn_s_barrier()
; #define PG8_SCHED __builtin_amdgcn_sched_barrier(0)
; template <class Epi>
; __device__ __forceinline__ void gemm_phase(LAS unsigned char* lds, const Gemm g, const StaticOrder& S, const Epi& E, const int tid) {
;     ...
;             PG8_WAIT_V(8); PG8_WAIT_L(0); PG8_BAR; PG8_MMA(1, 0, At, B0); PG8_MMA(1, 1, At, B1); PG8_BAR; PG8_SCHED;
;             PG8_LDB(B0, 1, 0); PG8_LDB(B1, 1, 1); PG8_SCHED; PG8_LDA(At, 1, 0); PG8_STAGE(PG8_SA(0, 1), a2 + hstepA, voffA);
;             PG8_WAIT_V(8); PG8_WAIT_L(0); PG8_BAR; PG8_MMA(0, 0, At, B0); PG8_MMA(0, 1, At, B1); PG8_BAR; PG8_SCHED;
	v_mfma_f32_16x16x32_bf16 v[60:63], v[124:127], v[160:163], v[60:63]
	v_mfma_f32_16x16x32_bf16 v[56:59], v[136:139], v[160:163], v[56:59]
	v_mfma_f32_16x16x32_bf16 v[44:47], v[124:127], v[168:171], v[44:47]
	v_mfma_f32_16x16x32_bf16 v[40:43], v[136:139], v[168:171], v[40:43]
	v_mfma_f32_16x16x32_bf16 v[28:31], v[124:127], v[202:205], v[28:31]
	v_mfma_f32_16x16x32_bf16 v[24:27], v[136:139], v[202:205], v[24:27]
	v_mfma_f32_16x16x32_bf16 v[12:15], v[124:127], v[210:213], v[12:15]
	v_mfma_f32_16x16x32_bf16 v[8:11], v[136:139], v[210:213], v[8:11]
	v_mfma_f32_16x16x32_bf16 v[60:63], v[128:131], v[164:167], v[60:63]
	v_mfma_f32_16x16x32_bf16 v[56:59], v[140:143], v[164:167], v[56:59]
	v_mfma_f32_16x16x32_bf16 v[44:47], v[128:131], v[172:175], v[44:47]
	v_mfma_f32_16x16x32_bf16 v[40:43], v[140:143], v[172:175], v[40:43]
	v_mfma_f32_16x16x32_bf16 v[28:31], v[128:131], v[206:209], v[28:31]
	v_mfma_f32_16x16x32_bf16 v[24:27], v[140:143], v[206:209], v[24:27]
	v_mfma_f32_16x16x32_bf16 v[12:15], v[128:131], v[214:217], v[12:15]
	v_mfma_f32_16x16x32_bf16 v[8:11], v[140:143], v[214:217], v[8:11]
	v_mfma_f32_16x16x32_bf16 v[52:55], v[144:147], v[160:163], v[52:55]
	v_mfma_f32_16x16x32_bf16 v[48:51], v[152:155], v[160:163], v[48:51]
	v_mfma_f32_16x16x32_bf16 v[36:39], v[144:147], v[168:171], v[36:39]
	v_mfma_f32_16x16x32_bf16 v[32:35], v[152:155], v[168:171], v[32:35]
	v_mfma_f32_16x16x32_bf16 v[20:23], v[144:147], v[202:205], v[20:23]
	v_mfma_f32_16x16x32_bf16 v[16:19], v[152:155], v[202:205], v[16:19]
	v_mfma_f32_16x16x32_bf16 v[4:7], v[144:147], v[210:213], v[4:7]
	v_mfma_f32_16x16x32_bf16 v[0:3], v[152:155], v[210:213], v[0:3]
	v_mfma_f32_16x16x32_bf16 v[52:55], v[148:151], v[164:167], v[52:55]
	v_mfma_f32_16x16x32_bf16 v[48:51], v[156:159], v[164:167], v[48:51]
	v_mfma_f32_16x16x32_bf16 v[36:39], v[148:151], v[172:175], v[36:39]
	v_mfma_f32_16x16x32_bf16 v[32:35], v[156:159], v[172:175], v[32:35]
	v_mfma_f32_16x16x32_bf16 v[20:23], v[148:151], v[206:209], v[20:23]
	v_mfma_f32_16x16x32_bf16 v[16:19], v[156:159], v[206:209], v[16:19]
	v_mfma_f32_16x16x32_bf16 v[4:7], v[148:151], v[214:217], v[4:7]
	v_mfma_f32_16x16x32_bf16 v[0:3], v[156:159], v[214:217], v[0:3]
	s_barrier
	s_add_i32 s80, 0, 0x18000
	s_add_i32 s81, 0, 0x1c000
	v_add_u32_e32 v140, s80, v225
	v_add_u32_e32 v156, s81, v225
	ds_read_b128 v[124:127], v140
	ds_read_b128 v[128:131], v140 offset:1024
	ds_read_b128 v[136:139], v140 offset:2048
	ds_read_b128 v[140:143], v140 offset:3072
	ds_read_b128 v[144:147], v156
	ds_read_b128 v[148:151], v156 offset:1024
	ds_read_b128 v[152:155], v156 offset:2048
	ds_read_b128 v[156:159], v156 offset:3072
	s_add_u32 s52, s52, s21
	s_addc_u32 s53, s53, 0
	s_mov_b32 m0, s55
	v_lshl_add_u64 v[230:231], s[52:53], 0, v[194:195]
	ds_read_b128 v[160:163], v226 offset:32768
	ds_read_b128 v[164:167], v226 offset:33792
	ds_read_b128 v[168:171], v226 offset:34816
	ds_read_b128 v[172:175], v226 offset:35840
	ds_read_b128 v[202:205], v226 offset:36864
	ds_read_b128 v[206:209], v226 offset:37888
	ds_read_b128 v[210:213], v226 offset:38912
	ds_read_b128 v[214:217], v226 offset:39936
	global_load_lds_dwordx4 v[230:231], off
	v_lshl_add_u64 v[230:231], s[52:53], 0, v[198:199]
	s_mov_b32 m0, s56
	s_nop 0
	global_load_lds_dwordx4 v[230:231], off
	s_waitcnt vmcnt(8)
	s_waitcnt lgkmcnt(0)
	s_barrier
	v_mfma_f32_16x16x32_bf16 v[132:135], v[124:127], v[160:163], v[132:135]
	v_mfma_f32_16x16x32_bf16 v[120:123], v[136:139], v[160:163], v[120:123]
	v_mfma_f32_16x16x32_bf16 v[108:111], v[124:127], v[168:171], v[108:111]
	v_mfma_f32_16x16x32_bf16 v[104:107], v[136:139], v[168:171], v[104:107]
	v_mfma_f32_16x16x32_bf16 v[92:95], v[124:127], v[202:205], v[92:95]
	v_mfma_f32_16x16x32_bf16 v[88:91], v[136:139], v[202:205], v[88:91]
	v_mfma_f32_16x16x32_bf16 v[76:79], v[124:127], v[210:213], v[76:79]
	v_mfma_f32_16x16x32_bf16 v[72:75], v[136:139], v[210:213], v[72:75]
	v_mfma_f32_16x16x32_bf16 v[132:135], v[128:131], v[164:167], v[132:135]
	v_mfma_f32_16x16x32_bf16 v[120:123], v[140:143], v[164:167], v[120:123]
	v_mfma_f32_16x16x32_bf16 v[108:111], v[128:131], v[172:175], v[108:111]
	v_mfma_f32_16x16x32_bf16 v[104:107], v[140:143], v[172:175], v[104:107]
	v_mfma_f32_16x16x32_bf16 v[92:95], v[128:131], v[206:209], v[92:95]
	v_mfma_f32_16x16x32_bf16 v[88:91], v[140:143], v[206:209], v[88:91]
	v_mfma_f32_16x16x32_bf16 v[76:79], v[128:131], v[214:217], v[76:79]
	v_mfma_f32_16x16x32_bf16 v[72:75], v[140:143], v[214:217], v[72:75]
	v_mfma_f32_16x16x32_bf16 v[116:119], v[144:147], v[160:163], v[116:119]
	v_mfma_f32_16x16x32_bf16 v[112:115], v[152:155], v[160:163], v[112:115]
	v_mfma_f32_16x16x32_bf16 v[100:103], v[144:147], v[168:171], v[100:103]
	v_mfma_f32_16x16x32_bf16 v[96:99], v[152:155], v[168:171], v[96:99]
	v_mfma_f32_16x16x32_bf16 v[84:87], v[144:147], v[202:205], v[84:87]
	v_mfma_f32_16x16x32_bf16 v[80:83], v[152:155], v[202:205], v[80:83]
	v_mfma_f32_16x16x32_bf16 v[68:71], v[144:147], v[210:213], v[68:71]
	v_mfma_f32_16x16x32_bf16 v[64:67], v[152:155], v[210:213], v[64:67]
	v_mfma_f32_16x16x32_bf16 v[116:119], v[148:151], v[164:167], v[116:119]
	v_mfma_f32_16x16x32_bf16 v[112:115], v[156:159], v[164:167], v[112:115]
	v_mfma_f32_16x16x32_bf16 v[100:103], v[148:151], v[172:175], v[100:103]
	v_mfma_f32_16x16x32_bf16 v[96:99], v[156:159], v[172:175], v[96:99]
	v_mfma_f32_16x16x32_bf16 v[84:87], v[148:151], v[206:209], v[84:87]
	v_mfma_f32_16x16x32_bf16 v[80:83], v[156:159], v[206:209], v[80:83]
	v_mfma_f32_16x16x32_bf16 v[68:71], v[148:151], v[214:217], v[68:71]
	v_mfma_f32_16x16x32_bf16 v[64:67], v[156:159], v[214:217], v[64:67]
	s_barrier
; #define PG8_STAGE(bufoff, gbase, voff) do { _Pragma("unroll") for (int _i = 0; _i < 2; ++_i) \
;         __builtin_amdgcn_global_load_lds((const unsigned*)((const char*)(gbase) + (voff)[_i]), (LAS unsigned*)(lds + (bufoff) + ldsw + _i * 8192), 16, 0, 0); } while (0)
; #define PG8_LDA(dst, b, h) do { _Pragma("unroll") for (int m = 0; m < 4; ++m) _Pragma("unroll") for (int k = 0; k < 2; ++k) dst[m][k] = *(const LAS bf16x8*)(lds + PG8_SA(b, h) + aoff + m * 2048 + k * 1024); } while (0)
; #define PG8_MMA(ai, bj, At, Bt) do { __builtin_amdgcn_s_setprio(1); _Pragma("unroll") for (int m = 0; m < 4; ++m) _Pragma("unroll") for (int n = 0; n < 2; ++n) _Pragma("unroll") for (int k = 0; k < 2; ++k) \
;         acc[ai][bj][m][n] = __builtin_amdgcn_mfma_f32_16x16x32_bf16(Bt[n][k], At[m][k], acc[ai][bj][m][n], 0, 0, 0); __builtin_amdgcn_s_setprio(0); } while (0)
; #define PG8_WAIT_V(n) asm volatile("s_waitcnt vmcnt(" #n ")" ::: "memory")
; #define PG8_WAIT_L(n) asm volatile("s_waitcnt lgkmcnt(" #n ")" ::: "memory")
; #define PG8_BAR __builtin_amdgcn_s_barrier()
; #define PG8_SCHED __builtin_amdgcn_sched_barrier(0)
; template <class Epi>
; __device__ __forceinline__ void gemm_phase(LAS unsigned char* lds, const Gemm g, const StaticOrder& S, const Epi& E, const int tid) {
;     ...
;             PG8_LDA(At, 1, 1); PG8_STAGE(PG8_SB(1, 0), b3, voffB); PG8_STAGE(PG8_SB(1, 1), b3 + hstepB, voffB); PG8_STAGE(PG8_SA(1, 0), a3, voffA);
;             PG8_WAIT_V(8); PG8_WAIT_L(0); PG8_BAR; PG8_MMA(1, 0, At, B0); PG8_MMA(1, 1, At, B1); PG8_BAR; PG8_SCHED;
;         }
	s_add_i32 s52, s80, s17
	v_lshl_add_u64 v[178:179], v[178:179], 0, s[36:37]
	s_mov_b32 m0, s52
	ds_read_b128 v[160:163], v226 offset:49152
	ds_read_b128 v[164:167], v226 offset:50176
	ds_read_b128 v[168:171], v226 offset:51200
	ds_read_b128 v[172:175], v226 offset:52224
	ds_read_b128 v[202:205], v226 offset:53248
	ds_read_b128 v[206:209], v226 offset:54272
	ds_read_b128 v[210:213], v226 offset:55296
	ds_read_b128 v[214:217], v226 offset:56320
	global_load_lds_dwordx4 v[178:179], off
	v_lshl_add_u64 v[178:179], v[180:181], 0, s[36:37]
	s_add_i32 m0, s52, 0x2000
	s_add_i32 s52, s81, s17
	global_load_lds_dwordx4 v[178:179], off
	v_lshl_add_u64 v[178:179], v[218:219], 0, s[36:37]
	s_mov_b32 m0, s52
	s_nop 0
	global_load_lds_dwordx4 v[178:179], off
	v_lshl_add_u64 v[178:179], v[228:229], 0, s[36:37]
	s_add_i32 m0, s52, 0x2000
	s_nop 0
	global_load_lds_dwordx4 v[178:179], off
	v_lshl_add_u64 v[178:179], s[28:29], 0, v[194:195]
	s_mov_b32 m0, s59
	s_nop 0
	global_load_lds_dwordx4 v[178:179], off
	v_lshl_add_u64 v[178:179], s[28:29], 0, v[198:199]
	s_mov_b32 m0, s60
	s_nop 0
	global_load_lds_dwordx4 v[178:179], off
	s_waitcnt vmcnt(8)
	s_waitcnt lgkmcnt(0)
	s_barrier
	v_mfma_f32_16x16x32_bf16 v[60:63], v[124:127], v[160:163], v[60:63]
	v_mfma_f32_16x16x32_bf16 v[56:59], v[136:139], v[160:163], v[56:59]
	v_mfma_f32_16x16x32_bf16 v[44:47], v[124:127], v[168:171], v[44:47]
	v_mfma_f32_16x16x32_bf16 v[40:43], v[136:139], v[168:171], v[40:43]
	v_mfma_f32_16x16x32_bf16 v[28:31], v[124:127], v[202:205], v[28:31]
	v_mfma_f32_16x16x32_bf16 v[24:27], v[136:139], v[202:205], v[24:27]
	v_mfma_f32_16x16x32_bf16 v[12:15], v[124:127], v[210:213], v[12:15]
	v_mfma_f32_16x16x32_bf16 v[8:11], v[136:139], v[210:213], v[8:11]
	v_mfma_f32_16x16x32_bf16 v[60:63], v[128:131], v[164:167], v[60:63]
	v_mfma_f32_16x16x32_bf16 v[56:59], v[140:143], v[164:167], v[56:59]
	v_mfma_f32_16x16x32_bf16 v[44:47], v[128:131], v[172:175], v[44:47]
	v_mfma_f32_16x16x32_bf16 v[40:43], v[140:143], v[172:175], v[40:43]
	v_mfma_f32_16x16x32_bf16 v[28:31], v[128:131], v[206:209], v[28:31]
	v_mfma_f32_16x16x32_bf16 v[24:27], v[140:143], v[206:209], v[24:27]
	v_mfma_f32_16x16x32_bf16 v[12:15], v[128:131], v[214:217], v[12:15]
	v_mfma_f32_16x16x32_bf16 v[8:11], v[140:143], v[214:217], v[8:11]
	v_mfma_f32_16x16x32_bf16 v[52:55], v[144:147], v[160:163], v[52:55]
	v_mfma_f32_16x16x32_bf16 v[48:51], v[152:155], v[160:163], v[48:51]
	v_mfma_f32_16x16x32_bf16 v[36:39], v[144:147], v[168:171], v[36:39]
	v_mfma_f32_16x16x32_bf16 v[32:35], v[152:155], v[168:171], v[32:35]
	v_mfma_f32_16x16x32_bf16 v[20:23], v[144:147], v[202:205], v[20:23]
	v_mfma_f32_16x16x32_bf16 v[16:19], v[152:155], v[202:205], v[16:19]
	v_mfma_f32_16x16x32_bf16 v[4:7], v[144:147], v[210:213], v[4:7]
	v_mfma_f32_16x16x32_bf16 v[0:3], v[152:155], v[210:213], v[0:3]
	v_mfma_f32_16x16x32_bf16 v[52:55], v[148:151], v[164:167], v[52:55]
	v_mfma_f32_16x16x32_bf16 v[48:51], v[156:159], v[164:167], v[48:51]
	v_mfma_f32_16x16x32_bf16 v[36:39], v[148:151], v[172:175], v[36:39]
	v_mfma_f32_16x16x32_bf16 v[32:35], v[156:159], v[172:175], v[32:35]
	v_mfma_f32_16x16x32_bf16 v[20:23], v[148:151], v[206:209], v[20:23]
	v_mfma_f32_16x16x32_bf16 v[16:19], v[156:159], v[206:209], v[16:19]
	v_mfma_f32_16x16x32_bf16 v[4:7], v[148:151], v[214:217], v[4:7]
	v_mfma_f32_16x16x32_bf16 v[0:3], v[156:159], v[214:217], v[0:3]
	s_barrier
	s_add_u32 s73, s73, 0x100
	s_addc_u32 s75, s75, 0
	s_cmp_ge_u32 s34, s58
	s_mov_b64 s[28:29], s[34:35]
	s_cbranch_scc0 .LBB0_393
	s_and_b64 vcc, exec, s[48:49]
	s_cbranch_vccz .LBB0_396
	s_barrier

; #define PG8_STAGE(bufoff, gbase, voff) do { _Pragma("unroll") for (int _i = 0; _i < 2; ++_i) \
;         __builtin_amdgcn_global_load_lds((const unsigned*)((const char*)(gbase) + (voff)[_i]), (LAS unsigned*)(lds + (bufoff) + ldsw + _i * 8192), 16, 0, 0); } while (0)
; #define PG8_LDA(dst, b, h) do { _Pragma("unroll") for (int m = 0; m < 4; ++m) _Pragma("unroll") for (int k = 0; k < 2; ++k) dst[m][k] = *(const LAS bf16x8*)(lds + PG8_SA(b, h) + aoff + m * 2048 + k * 1024); } while (0)
; #define PG8_LDB(dst, b, h) do { _Pragma("unroll") for (int n = 0; n < 2; ++n) _Pragma("unroll") for (int k = 0; k < 2; ++k) dst[n][k] = *(const LAS bf16x8*)(lds + PG8_SB(b, h) + boff + n * 2048 + k * 1024); } while (0)
; #define PG8_MMA(ai, bj, At, Bt) do { __builtin_amdgcn_s_setprio(1); _Pragma("unroll") for (int m = 0; m < 4; ++m) _Pragma("unroll") for (int n = 0; n < 2; ++n) _Pragma("unroll") for (int k = 0; k < 2; ++k) \
;         acc[ai][bj][m][n] = __builtin_amdgcn_mfma_f32_16x16x32_bf16(Bt[n][k], At[m][k], acc[ai][bj][m][n], 0, 0, 0); __builtin_amdgcn_s_setprio(0); } while (0)
; #define PG8_WAIT_V(n) asm volatile("s_waitcnt vmcnt(" #n ")" ::: "memory")
; #define PG8_WAIT_L(n) asm volatile("s_waitcnt lgkmcnt(" #n ")" ::: "memory")
; #define PG8_BAR __builtin_amdgcn_s_barrier()
; #define PG8_SCHED __builtin_amdgcn_sched_barrier(0)
; template <class Epi>
; __device__ __forceinline__ void gemm_phase(LAS unsigned char* lds, const Gemm g, const StaticOrder& S, const Epi& E, const int tid) {
;     ...
;         for (int t = 0; t < nt; t += 2) {
;             const bool last = (t == nt - 2);
;             const char* a1 = cA + (size_t)(t + 1) * kstepA;
;             const char* a2 = last ? nA : cA + (size_t)(t + 2) * kstepA; const char* b2 = last ? nB : cB + (size_t)(t + 2) * kstep;
;             const char* a3 = a2 + kstepA; const char* b3 = b2 + kstep;
;             PG8_LDB(B0, 0, 0); PG8_LDB(B1, 0, 1); PG8_SCHED; PG8_LDA(At, 0, 0); PG8_STAGE(PG8_SA(1, 1), a1 + hstepA, voffA);
;             PG8_WAIT_V(8); PG8_WAIT_L(0); PG8_BAR; PG8_MMA(0, 0, At, B0); PG8_MMA(0, 1, At, B1); PG8_BAR; PG8_SCHED;
;             PG8_LDA(At, 0, 1); PG8_STAGE(PG8_SB(0, 0), b2, voffB); PG8_STAGE(PG8_SB(0, 1), b2 + hstepB, voffB); PG8_STAGE(PG8_SA(0, 0), a2, voffA);
.LBB0_435:
	s_add_i32 s61, s44, 2
	s_add_u32 s62, s2, 0x800
	s_addc_u32 s45, s3, 0
	s_add_i32 s64, 0, 0x10000
	s_cmp_eq_u32 s51, s44
	s_cselect_b32 s45, s7, s45
	s_cselect_b32 s44, s6, s62
	s_cselect_b32 s63, s43, s60
	s_cselect_b32 s62, s42, s59
	s_add_i32 s65, 0, 0x14000
	v_add_u32_e32 v140, s64, v193
	v_add_u32_e32 v156, s65, v193
	ds_read_b128 v[128:131], v140
	ds_read_b128 v[132:135], v140 offset:1024
	ds_read_b128 v[136:139], v140 offset:2048
	ds_read_b128 v[140:143], v140 offset:3072
	ds_read_b128 v[144:147], v156
	ds_read_b128 v[148:151], v156 offset:1024
	ds_read_b128 v[152:155], v156 offset:2048
	ds_read_b128 v[156:159], v156 offset:3072
	v_lshl_add_u64 v[178:179], s[2:3], 0, v[168:169]
	s_add_i32 m0, s22, 0xc000
	ds_read_b128 v[172:175], v195
	ds_read_b128 v[196:199], v195 offset:1024
	ds_read_b128 v[202:205], v195 offset:2048
	ds_read_b128 v[206:209], v195 offset:3072
	ds_read_b128 v[210:213], v195 offset:4096
	ds_read_b128 v[214:217], v195 offset:5120
	ds_read_b128 v[226:229], v195 offset:6144
	ds_read_b128 v[230:233], v195 offset:7168
	global_load_lds_dwordx4 v[178:179], off
	v_lshl_add_u64 v[178:179], s[2:3], 0, v[170:171]
	s_add_i32 m0, s22, 0xe000
	s_nop 0
	global_load_lds_dwordx4 v[178:179], off
	s_waitcnt vmcnt(8)
	s_waitcnt lgkmcnt(0)
	s_barrier
	v_mfma_f32_16x16x32_bf16 v[124:127], v[128:131], v[172:175], v[124:127]
	v_mfma_f32_16x16x32_bf16 v[120:123], v[136:139], v[172:175], v[120:123]
	v_mfma_f32_16x16x32_bf16 v[108:111], v[128:131], v[202:205], v[108:111]
	v_mfma_f32_16x16x32_bf16 v[104:107], v[136:139], v[202:205], v[104:107]
	v_mfma_f32_16x16x32_bf16 v[92:95], v[128:131], v[210:213], v[92:95]
	v_mfma_f32_16x16x32_bf16 v[88:91], v[136:139], v[210:213], v[88:91]
	v_mfma_f32_16x16x32_bf16 v[76:79], v[128:131], v[226:229], v[76:79]
	v_mfma_f32_16x16x32_bf16 v[72:75], v[136:139], v[226:229], v[72:75]
	v_mfma_f32_16x16x32_bf16 v[124:127], v[132:135], v[196:199], v[124:127]
	v_mfma_f32_16x16x32_bf16 v[120:123], v[140:143], v[196:199], v[120:123]
	v_mfma_f32_16x16x32_bf16 v[108:111], v[132:135], v[206:209], v[108:111]
	v_mfma_f32_16x16x32_bf16 v[104:107], v[140:143], v[206:209], v[104:107]
	v_mfma_f32_16x16x32_bf16 v[92:95], v[132:135], v[214:217], v[92:95]
	v_mfma_f32_16x16x32_bf16 v[88:91], v[140:143], v[214:217], v[88:91]
	v_mfma_f32_16x16x32_bf16 v[76:79], v[132:135], v[230:233], v[76:79]
	v_mfma_f32_16x16x32_bf16 v[72:75], v[140:143], v[230:233], v[72:75]
	v_mfma_f32_16x16x32_bf16 v[116:119], v[144:147], v[172:175], v[116:119]
	v_mfma_f32_16x16x32_bf16 v[112:115], v[152:155], v[172:175], v[112:115]
	v_mfma_f32_16x16x32_bf16 v[100:103], v[144:147], v[202:205], v[100:103]
	v_mfma_f32_16x16x32_bf16 v[96:99], v[152:155], v[202:205], v[96:99]
	v_mfma_f32_16x16x32_bf16 v[84:87], v[144:147], v[210:213], v[84:87]
	v_mfma_f32_16x16x32_bf16 v[80:83], v[152:155], v[210:213], v[80:83]
	v_mfma_f32_16x16x32_bf16 v[68:71], v[144:147], v[226:229], v[68:71]
	v_mfma_f32_16x16x32_bf16 v[64:67], v[152:155], v[226:229], v[64:67]
	v_mfma_f32_16x16x32_bf16 v[116:119], v[148:151], v[196:199], v[116:119]
	v_mfma_f32_16x16x32_bf16 v[112:115], v[156:159], v[196:199], v[112:115]
	v_mfma_f32_16x16x32_bf16 v[100:103], v[148:151], v[206:209], v[100:103]
	v_mfma_f32_16x16x32_bf16 v[96:99], v[156:159], v[206:209], v[96:99]
	v_mfma_f32_16x16x32_bf16 v[84:87], v[148:151], v[214:217], v[84:87]
	v_mfma_f32_16x16x32_bf16 v[80:83], v[156:159], v[214:217], v[80:83]
	v_mfma_f32_16x16x32_bf16 v[68:71], v[148:151], v[230:233], v[68:71]
	v_mfma_f32_16x16x32_bf16 v[64:67], v[156:159], v[230:233], v[64:67]
	s_barrier
	s_add_i32 s64, s64, s21
	v_lshl_add_u64 v[178:179], s[62:63], 0, v[164:165]
	s_mov_b32 m0, s64
	ds_read_b128 v[172:175], v195 offset:16384
	ds_read_b128 v[196:199], v195 offset:17408
	ds_read_b128 v[202:205], v195 offset:18432
	ds_read_b128 v[206:209], v195 offset:19456
	ds_read_b128 v[210:213], v195 offset:20480
	ds_read_b128 v[214:217], v195 offset:21504
	ds_read_b128 v[226:229], v195 offset:22528
	ds_read_b128 v[230:233], v195 offset:23552
	global_load_lds_dwordx4 v[178:179], off
	s_add_i32 m0, s64, 0x2000
	v_lshl_add_u64 v[180:181], s[62:63], 0, v[162:163]
	s_add_u32 s62, s62, s8
	s_addc_u32 s63, s63, s9
	s_add_i32 s64, s65, s21
	global_load_lds_dwordx4 v[180:181], off
	v_lshl_add_u64 v[218:219], s[62:63], 0, v[164:165]
	s_mov_b32 m0, s64
	v_lshl_add_u64 v[234:235], s[62:63], 0, v[162:163]
	global_load_lds_dwordx4 v[218:219], off
	s_add_i32 m0, s64, 0x2000
	v_lshl_add_u64 v[236:237], s[44:45], 0, v[176:177]
	global_load_lds_dwordx4 v[234:235], off
	s_mov_b32 m0, s22
	v_lshl_add_u64 v[238:239], s[44:45], 0, v[160:161]
	global_load_lds_dwordx4 v[236:237], off
	s_mov_b32 m0, s23
	s_nop 0
	global_load_lds_dwordx4 v[238:239], off
	s_waitcnt vmcnt(8)
	s_waitcnt lgkmcnt(0)
	s_barrier
; #define PG8_STAGE(bufoff, gbase, voff) do { _Pragma("unroll") for (int _i = 0; _i < 2; ++_i) \
;         __builtin_amdgcn_global_load_lds((const unsigned*)((const char*)(gbase) + (voff)[_i]), (LAS unsigned*)(lds + (bufoff) + ldsw + _i * 8192), 16, 0, 0); } while (0)
; #define PG8_LDA(dst, b, h) do { _Pragma("unroll") for (int m = 0; m < 4; ++m) _Pragma("unroll") for (int k = 0; k < 2; ++k) dst[m][k] = *(const LAS bf16x8*)(lds + PG8_SA(b, h) + aoff + m * 2048 + k * 1024); } while (0)
; #define PG8_LDB(dst, b, h) do { _Pragma("unroll") for (int n = 0; n < 2; ++n) _Pragma("unroll") for (int k = 0; k < 2; ++k) dst[n][k] = *(const LAS bf16x8*)(lds + PG8_SB(b, h) + boff + n * 2048 + k * 1024); } while (0)
; #define PG8_MMA(ai, bj, At, Bt) do { __builtin_amdgcn_s_setprio(1); _Pragma("unroll") for (int m = 0; m < 4; ++m) _Pragma("unroll") for (int n = 0; n < 2; ++n) _Pragma("unroll") for (int k = 0; k < 2; ++k) \
;         acc[ai][bj][m][n] = __builtin_amdgcn_mfma_f32_16x16x32_bf16(Bt[n][k], At[m][k], acc[ai][bj][m][n], 0, 0, 0); __builtin_amdgcn_s_setprio(0); } while (0)
; #define PG8_WAIT_V(n) asm volatile("s_waitcnt vmcnt(" #n ")" ::: "memory")
; #define PG8_WAIT_L(n) asm volatile("s_waitcnt lgkmcnt(" #n ")" ::: "memory")
; #define PG8_BAR __builtin_amdgcn_s_barrier()
; #define PG8_SCHED __builtin_amdgcn_sched_barrier(0)
; template <class Epi>
; __device__ __forceinline__ void gemm_phase(LAS unsigned char* lds, const Gemm g, const StaticOrder& S, const Epi& E, const int tid) {
;     ...
;             PG8_WAIT_V(8); PG8_WAIT_L(0); PG8_BAR; PG8_MMA(1, 0, At, B0); PG8_MMA(1, 1, At, B1); PG8_BAR; PG8_SCHED;
;             PG8_LDB(B0, 1, 0); PG8_LDB(B1, 1, 1); PG8_SCHED; PG8_LDA(At, 1, 0); PG8_STAGE(PG8_SA(0, 1), a2 + hstepA, voffA);
;             PG8_WAIT_V(8); PG8_WAIT_L(0); PG8_BAR; PG8_MMA(0, 0, At, B0); PG8_MMA(0, 1, At, B1); PG8_BAR; PG8_SCHED;
	v_mfma_f32_16x16x32_bf16 v[60:63], v[128:131], v[172:175], v[60:63]
	v_mfma_f32_16x16x32_bf16 v[56:59], v[136:139], v[172:175], v[56:59]
	v_mfma_f32_16x16x32_bf16 v[44:47], v[128:131], v[202:205], v[44:47]
	v_mfma_f32_16x16x32_bf16 v[40:43], v[136:139], v[202:205], v[40:43]
	v_mfma_f32_16x16x32_bf16 v[28:31], v[128:131], v[210:213], v[28:31]
	v_mfma_f32_16x16x32_bf16 v[24:27], v[136:139], v[210:213], v[24:27]
	v_mfma_f32_16x16x32_bf16 v[12:15], v[128:131], v[226:229], v[12:15]
	v_mfma_f32_16x16x32_bf16 v[8:11], v[136:139], v[226:229], v[8:11]
	v_mfma_f32_16x16x32_bf16 v[60:63], v[132:135], v[196:199], v[60:63]
	v_mfma_f32_16x16x32_bf16 v[56:59], v[140:143], v[196:199], v[56:59]
	v_mfma_f32_16x16x32_bf16 v[44:47], v[132:135], v[206:209], v[44:47]
	v_mfma_f32_16x16x32_bf16 v[40:43], v[140:143], v[206:209], v[40:43]
	v_mfma_f32_16x16x32_bf16 v[28:31], v[132:135], v[214:217], v[28:31]
	v_mfma_f32_16x16x32_bf16 v[24:27], v[140:143], v[214:217], v[24:27]
	v_mfma_f32_16x16x32_bf16 v[12:15], v[132:135], v[230:233], v[12:15]
	v_mfma_f32_16x16x32_bf16 v[8:11], v[140:143], v[230:233], v[8:11]
	v_mfma_f32_16x16x32_bf16 v[52:55], v[144:147], v[172:175], v[52:55]
	v_mfma_f32_16x16x32_bf16 v[48:51], v[152:155], v[172:175], v[48:51]
	v_mfma_f32_16x16x32_bf16 v[36:39], v[144:147], v[202:205], v[36:39]
	v_mfma_f32_16x16x32_bf16 v[32:35], v[152:155], v[202:205], v[32:35]
	v_mfma_f32_16x16x32_bf16 v[20:23], v[144:147], v[210:213], v[20:23]
	v_mfma_f32_16x16x32_bf16 v[16:19], v[152:155], v[210:213], v[16:19]
	v_mfma_f32_16x16x32_bf16 v[4:7], v[144:147], v[226:229], v[4:7]
	v_mfma_f32_16x16x32_bf16 v[0:3], v[152:155], v[226:229], v[0:3]
	v_mfma_f32_16x16x32_bf16 v[52:55], v[148:151], v[196:199], v[52:55]
	v_mfma_f32_16x16x32_bf16 v[48:51], v[156:159], v[196:199], v[48:51]
	v_mfma_f32_16x16x32_bf16 v[36:39], v[148:151], v[206:209], v[36:39]
	v_mfma_f32_16x16x32_bf16 v[32:35], v[156:159], v[206:209], v[32:35]
	v_mfma_f32_16x16x32_bf16 v[20:23], v[148:151], v[214:217], v[20:23]
	v_mfma_f32_16x16x32_bf16 v[16:19], v[156:159], v[214:217], v[16:19]
	v_mfma_f32_16x16x32_bf16 v[4:7], v[148:151], v[230:233], v[4:7]
	v_mfma_f32_16x16x32_bf16 v[0:3], v[156:159], v[230:233], v[0:3]
	s_barrier
	s_add_i32 s62, 0, 0x18000
	s_add_i32 s63, 0, 0x1c000
	v_add_u32_e32 v140, s62, v193
	v_add_u32_e32 v156, s63, v193
	ds_read_b128 v[128:131], v140
	ds_read_b128 v[132:135], v140 offset:1024
	ds_read_b128 v[136:139], v140 offset:2048
	ds_read_b128 v[140:143], v140 offset:3072
	ds_read_b128 v[144:147], v156
	ds_read_b128 v[148:151], v156 offset:1024
	ds_read_b128 v[152:155], v156 offset:2048
	ds_read_b128 v[156:159], v156 offset:3072
	s_add_u32 s44, s44, s30
	s_addc_u32 s45, s45, 0
	s_mov_b32 m0, s46
	v_lshl_add_u64 v[240:241], s[44:45], 0, v[176:177]
	ds_read_b128 v[172:175], v195 offset:32768
	ds_read_b128 v[196:199], v195 offset:33792
	ds_read_b128 v[202:205], v195 offset:34816
	ds_read_b128 v[206:209], v195 offset:35840
	ds_read_b128 v[210:213], v195 offset:36864
	ds_read_b128 v[214:217], v195 offset:37888
	ds_read_b128 v[226:229], v195 offset:38912
	ds_read_b128 v[230:233], v195 offset:39936
	global_load_lds_dwordx4 v[240:241], off
	v_lshl_add_u64 v[240:241], s[44:45], 0, v[160:161]
	s_mov_b32 m0, s47
	s_nop 0
	global_load_lds_dwordx4 v[240:241], off
	s_waitcnt vmcnt(8)
	s_waitcnt lgkmcnt(0)
	s_barrier
	v_mfma_f32_16x16x32_bf16 v[124:127], v[128:131], v[172:175], v[124:127]
	v_mfma_f32_16x16x32_bf16 v[120:123], v[136:139], v[172:175], v[120:123]
	v_mfma_f32_16x16x32_bf16 v[108:111], v[128:131], v[202:205], v[108:111]
	v_mfma_f32_16x16x32_bf16 v[104:107], v[136:139], v[202:205], v[104:107]
	v_mfma_f32_16x16x32_bf16 v[92:95], v[128:131], v[210:213], v[92:95]
	v_mfma_f32_16x16x32_bf16 v[88:91], v[136:139], v[210:213], v[88:91]
	v_mfma_f32_16x16x32_bf16 v[76:79], v[128:131], v[226:229], v[76:79]
	v_mfma_f32_16x16x32_bf16 v[72:75], v[136:139], v[226:229], v[72:75]
	v_mfma_f32_16x16x32_bf16 v[124:127], v[132:135], v[196:199], v[124:127]
	v_mfma_f32_16x16x32_bf16 v[120:123], v[140:143], v[196:199], v[120:123]
	v_mfma_f32_16x16x32_bf16 v[108:111], v[132:135], v[206:209], v[108:111]
	v_mfma_f32_16x16x32_bf16 v[104:107], v[140:143], v[206:209], v[104:107]
	v_mfma_f32_16x16x32_bf16 v[92:95], v[132:135], v[214:217], v[92:95]
	v_mfma_f32_16x16x32_bf16 v[88:91], v[140:143], v[214:217], v[88:91]
	v_mfma_f32_16x16x32_bf16 v[76:79], v[132:135], v[230:233], v[76:79]
	v_mfma_f32_16x16x32_bf16 v[72:75], v[140:143], v[230:233], v[72:75]
	v_mfma_f32_16x16x32_bf16 v[116:119], v[144:147], v[172:175], v[116:119]
	v_mfma_f32_16x16x32_bf16 v[112:115], v[152:155], v[172:175], v[112:115]
	v_mfma_f32_16x16x32_bf16 v[100:103], v[144:147], v[202:205], v[100:103]
	v_mfma_f32_16x16x32_bf16 v[96:99], v[152:155], v[202:205], v[96:99]
	v_mfma_f32_16x16x32_bf16 v[84:87], v[144:147], v[210:213], v[84:87]
	v_mfma_f32_16x16x32_bf16 v[80:83], v[152:155], v[210:213], v[80:83]
	v_mfma_f32_16x16x32_bf16 v[68:71], v[144:147], v[226:229], v[68:71]
	v_mfma_f32_16x16x32_bf16 v[64:67], v[152:155], v[226:229], v[64:67]
	v_mfma_f32_16x16x32_bf16 v[116:119], v[148:151], v[196:199], v[116:119]
	v_mfma_f32_16x16x32_bf16 v[112:115], v[156:159], v[196:199], v[112:115]
	v_mfma_f32_16x16x32_bf16 v[100:103], v[148:151], v[206:209], v[100:103]
	v_mfma_f32_16x16x32_bf16 v[96:99], v[156:159], v[206:209], v[96:99]
	v_mfma_f32_16x16x32_bf16 v[84:87], v[148:151], v[214:217], v[84:87]
	v_mfma_f32_16x16x32_bf16 v[80:83], v[156:159], v[214:217], v[80:83]
	v_mfma_f32_16x16x32_bf16 v[68:71], v[148:151], v[230:233], v[68:71]
	v_mfma_f32_16x16x32_bf16 v[64:67], v[156:159], v[230:233], v[64:67]
	s_barrier
; #define PG8_STAGE(bufoff, gbase, voff) do { _Pragma("unroll") for (int _i = 0; _i < 2; ++_i) \
;         __builtin_amdgcn_global_load_lds((const unsigned*)((const char*)(gbase) + (voff)[_i]), (LAS unsigned*)(lds + (bufoff) + ldsw + _i * 8192), 16, 0, 0); } while (0)
; #define PG8_LDA(dst, b, h) do { _Pragma("unroll") for (int m = 0; m < 4; ++m) _Pragma("unroll") for (int k = 0; k < 2; ++k) dst[m][k] = *(const LAS bf16x8*)(lds + PG8_SA(b, h) + aoff + m * 2048 + k * 1024); } while (0)
; #define PG8_MMA(ai, bj, At, Bt) do { __builtin_amdgcn_s_setprio(1); _Pragma("unroll") for (int m = 0; m < 4; ++m) _Pragma("unroll") for (int n = 0; n < 2; ++n) _Pragma("unroll") for (int k = 0; k < 2; ++k) \
;         acc[ai][bj][m][n] = __builtin_amdgcn_mfma_f32_16x16x32_bf16(Bt[n][k], At[m][k], acc[ai][bj][m][n], 0, 0, 0); __builtin_amdgcn_s_setprio(0); } while (0)
; #define PG8_WAIT_V(n) asm volatile("s_waitcnt vmcnt(" #n ")" ::: "memory")
; #define PG8_WAIT_L(n) asm volatile("s_waitcnt lgkmcnt(" #n ")" ::: "memory")
; #define PG8_BAR __builtin_amdgcn_s_barrier()
; #define PG8_SCHED __builtin_amdgcn_sched_barrier(0)
; template <class Epi>
; __device__ __forceinline__ void gemm_phase(LAS unsigned char* lds, const Gemm g, const StaticOrder& S, const Epi& E, const int tid) {
;     ...
;             PG8_LDA(At, 1, 1); PG8_STAGE(PG8_SB(1, 0), b3, voffB); PG8_STAGE(PG8_SB(1, 1), b3 + hstepB, voffB); PG8_STAGE(PG8_SA(1, 0), a3, voffA);
;             PG8_WAIT_V(8); PG8_WAIT_L(0); PG8_BAR; PG8_MMA(1, 0, At, B0); PG8_MMA(1, 1, At, B1); PG8_BAR; PG8_SCHED;
;         }
	s_add_i32 s44, s62, s21
	v_lshl_add_u64 v[178:179], v[178:179], 0, s[36:37]
	s_mov_b32 m0, s44
	ds_read_b128 v[172:175], v195 offset:49152
	ds_read_b128 v[196:199], v195 offset:50176
	ds_read_b128 v[202:205], v195 offset:51200
	ds_read_b128 v[206:209], v195 offset:52224
	ds_read_b128 v[210:213], v195 offset:53248
	ds_read_b128 v[214:217], v195 offset:54272
	ds_read_b128 v[226:229], v195 offset:55296
	ds_read_b128 v[230:233], v195 offset:56320
	global_load_lds_dwordx4 v[178:179], off
	v_lshl_add_u64 v[178:179], v[180:181], 0, s[36:37]
	s_add_i32 m0, s44, 0x2000
	s_add_i32 s44, s63, s21
	global_load_lds_dwordx4 v[178:179], off
	v_lshl_add_u64 v[178:179], v[218:219], 0, s[36:37]
	s_mov_b32 m0, s44
	s_nop 0
	global_load_lds_dwordx4 v[178:179], off
	v_lshl_add_u64 v[178:179], v[234:235], 0, s[36:37]
	s_add_i32 m0, s44, 0x2000
	s_nop 0
	global_load_lds_dwordx4 v[178:179], off
	v_lshl_add_u64 v[178:179], v[236:237], 0, s[76:77]
	s_mov_b32 m0, s49
	s_nop 0
	global_load_lds_dwordx4 v[178:179], off
	v_lshl_add_u64 v[178:179], v[238:239], 0, s[76:77]
	s_mov_b32 m0, s50
	s_nop 0
	global_load_lds_dwordx4 v[178:179], off
	s_waitcnt vmcnt(8)
	s_waitcnt lgkmcnt(0)
	s_barrier
	v_mfma_f32_16x16x32_bf16 v[60:63], v[128:131], v[172:175], v[60:63]
	v_mfma_f32_16x16x32_bf16 v[56:59], v[136:139], v[172:175], v[56:59]
	v_mfma_f32_16x16x32_bf16 v[44:47], v[128:131], v[202:205], v[44:47]
	v_mfma_f32_16x16x32_bf16 v[40:43], v[136:139], v[202:205], v[40:43]
	v_mfma_f32_16x16x32_bf16 v[28:31], v[128:131], v[210:213], v[28:31]
	v_mfma_f32_16x16x32_bf16 v[24:27], v[136:139], v[210:213], v[24:27]
	v_mfma_f32_16x16x32_bf16 v[12:15], v[128:131], v[226:229], v[12:15]
	v_mfma_f32_16x16x32_bf16 v[8:11], v[136:139], v[226:229], v[8:11]
	v_mfma_f32_16x16x32_bf16 v[60:63], v[132:135], v[196:199], v[60:63]
	v_mfma_f32_16x16x32_bf16 v[56:59], v[140:143], v[196:199], v[56:59]
	v_mfma_f32_16x16x32_bf16 v[44:47], v[132:135], v[206:209], v[44:47]
	v_mfma_f32_16x16x32_bf16 v[40:43], v[140:143], v[206:209], v[40:43]
	v_mfma_f32_16x16x32_bf16 v[28:31], v[132:135], v[214:217], v[28:31]
	v_mfma_f32_16x16x32_bf16 v[24:27], v[140:143], v[214:217], v[24:27]
	v_mfma_f32_16x16x32_bf16 v[12:15], v[132:135], v[230:233], v[12:15]
	v_mfma_f32_16x16x32_bf16 v[8:11], v[140:143], v[230:233], v[8:11]
	v_mfma_f32_16x16x32_bf16 v[52:55], v[144:147], v[172:175], v[52:55]
	v_mfma_f32_16x16x32_bf16 v[48:51], v[152:155], v[172:175], v[48:51]
	v_mfma_f32_16x16x32_bf16 v[36:39], v[144:147], v[202:205], v[36:39]
	v_mfma_f32_16x16x32_bf16 v[32:35], v[152:155], v[202:205], v[32:35]
	v_mfma_f32_16x16x32_bf16 v[20:23], v[144:147], v[210:213], v[20:23]
	v_mfma_f32_16x16x32_bf16 v[16:19], v[152:155], v[210:213], v[16:19]
	v_mfma_f32_16x16x32_bf16 v[4:7], v[144:147], v[226:229], v[4:7]
	v_mfma_f32_16x16x32_bf16 v[0:3], v[152:155], v[226:229], v[0:3]
	v_mfma_f32_16x16x32_bf16 v[52:55], v[148:151], v[196:199], v[52:55]
	v_mfma_f32_16x16x32_bf16 v[48:51], v[156:159], v[196:199], v[48:51]
	v_mfma_f32_16x16x32_bf16 v[36:39], v[148:151], v[206:209], v[36:39]
	v_mfma_f32_16x16x32_bf16 v[32:35], v[156:159], v[206:209], v[32:35]
	v_mfma_f32_16x16x32_bf16 v[20:23], v[148:151], v[214:217], v[20:23]
	v_mfma_f32_16x16x32_bf16 v[16:19], v[156:159], v[214:217], v[16:19]
	v_mfma_f32_16x16x32_bf16 v[4:7], v[148:151], v[230:233], v[4:7]
	v_mfma_f32_16x16x32_bf16 v[0:3], v[156:159], v[230:233], v[0:3]
	s_barrier
	s_add_u32 s59, s59, 0x100
	s_addc_u32 s60, s60, 0
	s_add_u32 s2, s2, 0x1000
	s_addc_u32 s3, s3, 0
	s_cmp_ge_u32 s61, s48
	s_mov_b32 s44, s61
	s_cbranch_scc0 .LBB0_435
	s_and_b64 vcc, exec, s[40:41]
	s_cbranch_vccz .LBB0_438
	s_barrier

; #define PG8_STAGE(bufoff, gbase, voff) do { _Pragma("unroll") for (int _i = 0; _i < 2; ++_i) \
;         __builtin_amdgcn_global_load_lds((const unsigned*)((const char*)(gbase) + (voff)[_i]), (LAS unsigned*)(lds + (bufoff) + ldsw + _i * 8192), 16, 0, 0); } while (0)
; #define PG8_LDA(dst, b, h) do { _Pragma("unroll") for (int m = 0; m < 4; ++m) _Pragma("unroll") for (int k = 0; k < 2; ++k) dst[m][k] = *(const LAS bf16x8*)(lds + PG8_SA(b, h) + aoff + m * 2048 + k * 1024); } while (0)
; #define PG8_LDB(dst, b, h) do { _Pragma("unroll") for (int n = 0; n < 2; ++n) _Pragma("unroll") for (int k = 0; k < 2; ++k) dst[n][k] = *(const LAS bf16x8*)(lds + PG8_SB(b, h) + boff + n * 2048 + k * 1024); } while (0)
; #define PG8_MMA(ai, bj, At, Bt) do { __builtin_amdgcn_s_setprio(1); _Pragma("unroll") for (int m = 0; m < 4; ++m) _Pragma("unroll") for (int n = 0; n < 2; ++n) _Pragma("unroll") for (int k = 0; k < 2; ++k) \
;         acc[ai][bj][m][n] = __builtin_amdgcn_mfma_f32_16x16x32_bf16(Bt[n][k], At[m][k], acc[ai][bj][m][n], 0, 0, 0); __builtin_amdgcn_s_setprio(0); } while (0)
; #define PG8_WAIT_V(n) asm volatile("s_waitcnt vmcnt(" #n ")" ::: "memory")
; template <class Epi>
; __device__ __forceinline__ void gemm_phase(LAS unsigned char* lds, const Gemm g, const StaticOrder& S, const Epi& E, const int tid) {
;     ...
;         const char* nA = has_next ? (const char*)g.A + (size_t)nxt.pm * tstepA + (size_t)nxt.pn * pnoffA : cA; const char* nB = has_next ? (const char*)g.Bt + (size_t)nxt.pn * tstepB : cB;
;         for (int t = 0; t < nt; t += 2) {
;             const bool last = (t == nt - 2);
;             const char* a1 = cA + (size_t)(t + 1) * kstepA;
;             const char* a2 = last ? nA : cA + (size_t)(t + 2) * kstepA; const char* b2 = last ? nB : cB + (size_t)(t + 2) * kstep;
;             const char* a3 = a2 + kstepA; const char* b3 = b2 + kstep;
;             PG8_LDB(B0, 0, 0); PG8_LDB(B1, 0, 1); PG8_SCHED; PG8_LDA(At, 0, 0); PG8_STAGE(PG8_SA(1, 1), a1 + hstepA, voffA);
;             PG8_WAIT_V(8); PG8_WAIT_L(0); PG8_BAR; PG8_MMA(0, 0, At, B0); PG8_MMA(0, 1, At, B1); PG8_BAR; PG8_SCHED;
;             PG8_LDA(At, 0, 1); PG8_STAGE(PG8_SB(0, 0), b2, voffB); PG8_STAGE(PG8_SB(0, 1), b2 + hstepB, voffB); PG8_STAGE(PG8_SA(0, 0), a2, voffA);
;             PG8_WAIT_V(8); PG8_WAIT_L(0); PG8_BAR; PG8_MMA(1, 0, At, B0); PG8_MMA(1, 1, At, B1); PG8_BAR; PG8_SCHED;
.LBB0_452:
	s_ashr_i32 s13, s12, 31
	s_lshl_b64 s[14:15], s[12:13], 19
	s_add_u32 s14, s24, s14
	s_addc_u32 s15, s25, s15
	s_and_b64 s[16:17], s[4:5], exec
	s_cselect_b32 s13, s15, s3
	s_cselect_b32 s51, s14, s2
	s_ashr_i32 s11, s10, 31
	s_lshl_b64 s[16:17], s[10:11], 19
	s_add_u32 s16, s20, s16
	s_addc_u32 s17, s21, s17
	s_and_b64 s[34:35], s[4:5], exec
	s_cselect_b32 s11, s17, s29
	s_cselect_b32 s52, s16, s28
	s_add_u32 s53, s28, 0x100
	s_addc_u32 s54, s29, 0
	s_mov_b32 s55, -2
	s_add_u32 s28, s2, 0x1000
	s_addc_u32 s29, s3, 0
	s_add_i32 s56, 0, 0x10000
	s_cmp_eq_u32 s55, 12
	s_cselect_b32 s41, s13, s29
	s_cselect_b32 s40, s51, s28
	v_add_u32_e32 v145, s56, v143
	s_cselect_b32 s35, s11, s54
	s_cselect_b32 s34, s52, s53
	s_add_i32 s57, 0, 0x14000
	ds_read_b128 v[146:149], v145
	ds_read_b128 v[150:153], v145 offset:1024
	ds_read_b128 v[154:157], v145 offset:2048
	ds_read_b128 v[158:161], v145 offset:3072
	v_add_u32_e32 v145, s57, v143
	ds_read_b128 v[162:165], v145
	ds_read_b128 v[166:169], v145 offset:1024
	ds_read_b128 v[170:173], v145 offset:2048
	ds_read_b128 v[194:197], v145 offset:3072
	v_lshl_add_u64 v[174:175], s[2:3], 0, v[138:139]
	s_add_i32 m0, s23, 0xc000
	ds_read_b128 v[202:205], v144
	ds_read_b128 v[206:209], v144 offset:1024
	ds_read_b128 v[210:213], v144 offset:2048
	ds_read_b128 v[214:217], v144 offset:3072
	ds_read_b128 v[226:229], v144 offset:4096
	ds_read_b128 v[230:233], v144 offset:5120
	ds_read_b128 v[234:237], v144 offset:6144
	ds_read_b128 v[238:241], v144 offset:7168
	global_load_lds_dwordx4 v[174:175], off
	v_lshl_add_u64 v[174:175], s[2:3], 0, v[140:141]
	s_add_i32 m0, s23, 0xe000
	s_nop 0
	global_load_lds_dwordx4 v[174:175], off
	s_waitcnt vmcnt(8)
	s_waitcnt lgkmcnt(0)
	s_barrier
	v_mfma_f32_16x16x32_bf16 v[124:127], v[146:149], v[202:205], 0
	v_mfma_f32_16x16x32_bf16 v[116:119], v[154:157], v[202:205], 0
	v_mfma_f32_16x16x32_bf16 v[108:111], v[146:149], v[210:213], 0
	v_mfma_f32_16x16x32_bf16 v[100:103], v[154:157], v[210:213], 0
	v_mfma_f32_16x16x32_bf16 v[92:95], v[146:149], v[226:229], 0
	v_mfma_f32_16x16x32_bf16 v[84:87], v[154:157], v[226:229], 0
	v_mfma_f32_16x16x32_bf16 v[76:79], v[146:149], v[234:237], 0
	v_mfma_f32_16x16x32_bf16 v[68:71], v[154:157], v[234:237], 0
	v_mfma_f32_16x16x32_bf16 v[124:127], v[150:153], v[206:209], v[124:127]
	v_mfma_f32_16x16x32_bf16 v[116:119], v[158:161], v[206:209], v[116:119]
	v_mfma_f32_16x16x32_bf16 v[108:111], v[150:153], v[214:217], v[108:111]
	v_mfma_f32_16x16x32_bf16 v[100:103], v[158:161], v[214:217], v[100:103]
	v_mfma_f32_16x16x32_bf16 v[92:95], v[150:153], v[230:233], v[92:95]
	v_mfma_f32_16x16x32_bf16 v[84:87], v[158:161], v[230:233], v[84:87]
	v_mfma_f32_16x16x32_bf16 v[76:79], v[150:153], v[238:241], v[76:79]
	v_mfma_f32_16x16x32_bf16 v[68:71], v[158:161], v[238:241], v[68:71]
	v_mfma_f32_16x16x32_bf16 v[120:123], v[162:165], v[202:205], 0
	v_mfma_f32_16x16x32_bf16 v[112:115], v[170:173], v[202:205], 0
	v_mfma_f32_16x16x32_bf16 v[104:107], v[162:165], v[210:213], 0
	v_mfma_f32_16x16x32_bf16 v[96:99], v[170:173], v[210:213], 0
	v_mfma_f32_16x16x32_bf16 v[88:91], v[162:165], v[226:229], 0
	v_mfma_f32_16x16x32_bf16 v[80:83], v[170:173], v[226:229], 0
	v_mfma_f32_16x16x32_bf16 v[72:75], v[162:165], v[234:237], 0
	v_mfma_f32_16x16x32_bf16 v[64:67], v[170:173], v[234:237], 0
	v_mfma_f32_16x16x32_bf16 v[120:123], v[166:169], v[206:209], v[120:123]
	v_mfma_f32_16x16x32_bf16 v[112:115], v[194:197], v[206:209], v[112:115]
	v_mfma_f32_16x16x32_bf16 v[104:107], v[166:169], v[214:217], v[104:107]
	v_mfma_f32_16x16x32_bf16 v[96:99], v[194:197], v[214:217], v[96:99]
	v_mfma_f32_16x16x32_bf16 v[88:91], v[166:169], v[230:233], v[88:91]
	v_mfma_f32_16x16x32_bf16 v[80:83], v[194:197], v[230:233], v[80:83]
	v_mfma_f32_16x16x32_bf16 v[72:75], v[166:169], v[238:241], v[72:75]
	v_mfma_f32_16x16x32_bf16 v[64:67], v[194:197], v[238:241], v[64:67]
	s_barrier
	s_lshl_b32 s100, s50, 14
	s_add_u32 s100, s82, s100
	s_addc_u32 s101, s83, 0
	s_lshl_b32 m0, s22, 1
	s_add_i32 m0, m0, 0x20800
	s_nop 0
	global_load_lds_dwordx4 v193, s[100:101]
	global_load_lds_dwordx4 v193, s[100:101] offset:1024
	s_add_i32 s2, s56, s22
	v_lshl_add_u64 v[174:175], s[34:35], 0, v[176:177]
	s_mov_b32 m0, s2
	ds_read_b128 v[202:205], v144 offset:16384
	ds_read_b128 v[206:209], v144 offset:17408
	ds_read_b128 v[210:213], v144 offset:18432
	ds_read_b128 v[214:217], v144 offset:19456
	ds_read_b128 v[226:229], v144 offset:20480
	ds_read_b128 v[230:233], v144 offset:21504
	ds_read_b128 v[234:237], v144 offset:22528
	ds_read_b128 v[238:241], v144 offset:23552
	global_load_lds_dwordx4 v[174:175], off
	s_add_i32 m0, s2, 0x2000
	s_add_u32 s2, s34, 0x40000
	v_lshl_add_u64 v[178:179], s[34:35], 0, v[128:129]
	s_addc_u32 s3, s35, 0
	s_add_i32 s56, s57, s22
	global_load_lds_dwordx4 v[178:179], off
	v_lshl_add_u64 v[180:181], s[2:3], 0, v[176:177]
	s_mov_b32 m0, s56
	v_lshl_add_u64 v[198:199], s[40:41], 0, v[130:131]
	global_load_lds_dwordx4 v[180:181], off
	v_lshl_add_u64 v[180:181], s[2:3], 0, v[128:129]
	s_add_i32 m0, s56, 0x2000
	s_nop 0
	global_load_lds_dwordx4 v[180:181], off
	v_lshl_add_u64 v[180:181], s[40:41], 0, v[132:133]
	s_mov_b32 m0, s23
	s_nop 0
	global_load_lds_dwordx4 v[180:181], off
	s_mov_b32 m0, s30
	s_nop 0
	global_load_lds_dwordx4 v[198:199], off
	s_waitcnt vmcnt(8)
	s_waitcnt lgkmcnt(0)
	s_barrier
; #define PG8_STAGE(bufoff, gbase, voff) do { _Pragma("unroll") for (int _i = 0; _i < 2; ++_i) \
;         __builtin_amdgcn_global_load_lds((const unsigned*)((const char*)(gbase) + (voff)[_i]), (LAS unsigned*)(lds + (bufoff) + ldsw + _i * 8192), 16, 0, 0); } while (0)
; #define PG8_LDA(dst, b, h) do { _Pragma("unroll") for (int m = 0; m < 4; ++m) _Pragma("unroll") for (int k = 0; k < 2; ++k) dst[m][k] = *(const LAS bf16x8*)(lds + PG8_SA(b, h) + aoff + m * 2048 + k * 1024); } while (0)
; #define PG8_LDB(dst, b, h) do { _Pragma("unroll") for (int n = 0; n < 2; ++n) _Pragma("unroll") for (int k = 0; k < 2; ++k) dst[n][k] = *(const LAS bf16x8*)(lds + PG8_SB(b, h) + boff + n * 2048 + k * 1024); } while (0)
; #define PG8_MMA(ai, bj, At, Bt) do { __builtin_amdgcn_s_setprio(1); _Pragma("unroll") for (int m = 0; m < 4; ++m) _Pragma("unroll") for (int n = 0; n < 2; ++n) _Pragma("unroll") for (int k = 0; k < 2; ++k) \
;         acc[ai][bj][m][n] = __builtin_amdgcn_mfma_f32_16x16x32_bf16(Bt[n][k], At[m][k], acc[ai][bj][m][n], 0, 0, 0); __builtin_amdgcn_s_setprio(0); } while (0)
; #define PG8_WAIT_V(n) asm volatile("s_waitcnt vmcnt(" #n ")" ::: "memory")
; #define PG8_WAIT_L(n) asm volatile("s_waitcnt lgkmcnt(" #n ")" ::: "memory")
; #define PG8_BAR __builtin_amdgcn_s_barrier()
; #define PG8_SCHED __builtin_amdgcn_sched_barrier(0)
; template <class Epi>
; __device__ __forceinline__ void gemm_phase(LAS unsigned char* lds, const Gemm g, const StaticOrder& S, const Epi& E, const int tid) {
;     ...
;             PG8_WAIT_V(8); PG8_WAIT_L(0); PG8_BAR; PG8_MMA(1, 0, At, B0); PG8_MMA(1, 1, At, B1); PG8_BAR; PG8_SCHED;
;             PG8_LDB(B0, 1, 0); PG8_LDB(B1, 1, 1); PG8_SCHED; PG8_LDA(At, 1, 0); PG8_STAGE(PG8_SA(0, 1), a2 + hstepA, voffA);
;             PG8_WAIT_V(8); PG8_WAIT_L(0); PG8_BAR; PG8_MMA(0, 0, At, B0); PG8_MMA(0, 1, At, B1); PG8_BAR; PG8_SCHED;
	v_mfma_f32_16x16x32_bf16 v[60:63], v[146:149], v[202:205], 0
	v_mfma_f32_16x16x32_bf16 v[52:55], v[154:157], v[202:205], 0
	v_mfma_f32_16x16x32_bf16 v[44:47], v[146:149], v[210:213], 0
	v_mfma_f32_16x16x32_bf16 v[36:39], v[154:157], v[210:213], 0
	v_mfma_f32_16x16x32_bf16 v[28:31], v[146:149], v[226:229], 0
	v_mfma_f32_16x16x32_bf16 v[20:23], v[154:157], v[226:229], 0
	v_mfma_f32_16x16x32_bf16 v[12:15], v[146:149], v[234:237], 0
	v_mfma_f32_16x16x32_bf16 v[4:7], v[154:157], v[234:237], 0
	v_mfma_f32_16x16x32_bf16 v[60:63], v[150:153], v[206:209], v[60:63]
	v_mfma_f32_16x16x32_bf16 v[52:55], v[158:161], v[206:209], v[52:55]
	v_mfma_f32_16x16x32_bf16 v[44:47], v[150:153], v[214:217], v[44:47]
	v_mfma_f32_16x16x32_bf16 v[36:39], v[158:161], v[214:217], v[36:39]
	v_mfma_f32_16x16x32_bf16 v[28:31], v[150:153], v[230:233], v[28:31]
	v_mfma_f32_16x16x32_bf16 v[20:23], v[158:161], v[230:233], v[20:23]
	v_mfma_f32_16x16x32_bf16 v[12:15], v[150:153], v[238:241], v[12:15]
	v_mfma_f32_16x16x32_bf16 v[4:7], v[158:161], v[238:241], v[4:7]
	v_mfma_f32_16x16x32_bf16 v[56:59], v[162:165], v[202:205], 0
	v_mfma_f32_16x16x32_bf16 v[48:51], v[170:173], v[202:205], 0
	v_mfma_f32_16x16x32_bf16 v[40:43], v[162:165], v[210:213], 0
	v_mfma_f32_16x16x32_bf16 v[32:35], v[170:173], v[210:213], 0
	v_mfma_f32_16x16x32_bf16 v[24:27], v[162:165], v[226:229], 0
	v_mfma_f32_16x16x32_bf16 v[16:19], v[170:173], v[226:229], 0
	v_mfma_f32_16x16x32_bf16 v[8:11], v[162:165], v[234:237], 0
	v_mfma_f32_16x16x32_bf16 v[0:3], v[170:173], v[234:237], 0
	v_mfma_f32_16x16x32_bf16 v[56:59], v[166:169], v[206:209], v[56:59]
	v_mfma_f32_16x16x32_bf16 v[48:51], v[194:197], v[206:209], v[48:51]
	v_mfma_f32_16x16x32_bf16 v[40:43], v[166:169], v[214:217], v[40:43]
	v_mfma_f32_16x16x32_bf16 v[32:35], v[194:197], v[214:217], v[32:35]
	v_mfma_f32_16x16x32_bf16 v[24:27], v[166:169], v[230:233], v[24:27]
	v_mfma_f32_16x16x32_bf16 v[16:19], v[194:197], v[230:233], v[16:19]
	v_mfma_f32_16x16x32_bf16 v[8:11], v[166:169], v[238:241], v[8:11]
	v_mfma_f32_16x16x32_bf16 v[0:3], v[194:197], v[238:241], v[0:3]
	s_barrier
	s_add_i32 s56, 0, 0x18000
	v_add_u32_e32 v145, s56, v143
	s_add_i32 s57, 0, 0x1c000
	ds_read_b128 v[146:149], v145
	ds_read_b128 v[150:153], v145 offset:1024
	ds_read_b128 v[154:157], v145 offset:2048
	ds_read_b128 v[158:161], v145 offset:3072
	v_add_u32_e32 v145, s57, v143
	ds_read_b128 v[162:165], v145
	ds_read_b128 v[166:169], v145 offset:1024
	ds_read_b128 v[170:173], v145 offset:2048
	ds_read_b128 v[194:197], v145 offset:3072
	s_add_u32 s2, s40, 0x40000
	s_addc_u32 s3, s41, 0
	s_mov_b32 m0, s42
	v_lshl_add_u64 v[218:219], s[2:3], 0, v[132:133]
	ds_read_b128 v[202:205], v144 offset:32768
	ds_read_b128 v[206:209], v144 offset:33792
	ds_read_b128 v[210:213], v144 offset:34816
	ds_read_b128 v[214:217], v144 offset:35840
	ds_read_b128 v[226:229], v144 offset:36864
	ds_read_b128 v[230:233], v144 offset:37888
	ds_read_b128 v[234:237], v144 offset:38912
	ds_read_b128 v[238:241], v144 offset:39936
	global_load_lds_dwordx4 v[218:219], off
	v_lshl_add_u64 v[218:219], s[2:3], 0, v[130:131]
	s_mov_b32 m0, s43
	s_nop 0
	global_load_lds_dwordx4 v[218:219], off
	s_waitcnt vmcnt(8)
	s_waitcnt lgkmcnt(0)
	s_barrier
	v_mfma_f32_16x16x32_bf16 v[124:127], v[146:149], v[202:205], v[124:127]
	v_mfma_f32_16x16x32_bf16 v[116:119], v[154:157], v[202:205], v[116:119]
	v_mfma_f32_16x16x32_bf16 v[108:111], v[146:149], v[210:213], v[108:111]
	v_mfma_f32_16x16x32_bf16 v[100:103], v[154:157], v[210:213], v[100:103]
	v_mfma_f32_16x16x32_bf16 v[92:95], v[146:149], v[226:229], v[92:95]
	v_mfma_f32_16x16x32_bf16 v[84:87], v[154:157], v[226:229], v[84:87]
	v_mfma_f32_16x16x32_bf16 v[76:79], v[146:149], v[234:237], v[76:79]
	v_mfma_f32_16x16x32_bf16 v[68:71], v[154:157], v[234:237], v[68:71]
	v_mfma_f32_16x16x32_bf16 v[124:127], v[150:153], v[206:209], v[124:127]
	v_mfma_f32_16x16x32_bf16 v[116:119], v[158:161], v[206:209], v[116:119]
	v_mfma_f32_16x16x32_bf16 v[108:111], v[150:153], v[214:217], v[108:111]
	v_mfma_f32_16x16x32_bf16 v[100:103], v[158:161], v[214:217], v[100:103]
	v_mfma_f32_16x16x32_bf16 v[92:95], v[150:153], v[230:233], v[92:95]
	v_mfma_f32_16x16x32_bf16 v[84:87], v[158:161], v[230:233], v[84:87]
	v_mfma_f32_16x16x32_bf16 v[76:79], v[150:153], v[238:241], v[76:79]
	v_mfma_f32_16x16x32_bf16 v[68:71], v[158:161], v[238:241], v[68:71]
	v_mfma_f32_16x16x32_bf16 v[120:123], v[162:165], v[202:205], v[120:123]
	v_mfma_f32_16x16x32_bf16 v[112:115], v[170:173], v[202:205], v[112:115]
	v_mfma_f32_16x16x32_bf16 v[104:107], v[162:165], v[210:213], v[104:107]
	v_mfma_f32_16x16x32_bf16 v[96:99], v[170:173], v[210:213], v[96:99]
	v_mfma_f32_16x16x32_bf16 v[88:91], v[162:165], v[226:229], v[88:91]
	v_mfma_f32_16x16x32_bf16 v[80:83], v[170:173], v[226:229], v[80:83]
	v_mfma_f32_16x16x32_bf16 v[72:75], v[162:165], v[234:237], v[72:75]
	v_mfma_f32_16x16x32_bf16 v[64:67], v[170:173], v[234:237], v[64:67]
	v_mfma_f32_16x16x32_bf16 v[120:123], v[166:169], v[206:209], v[120:123]
	v_mfma_f32_16x16x32_bf16 v[112:115], v[194:197], v[206:209], v[112:115]
	v_mfma_f32_16x16x32_bf16 v[104:107], v[166:169], v[214:217], v[104:107]
	v_mfma_f32_16x16x32_bf16 v[96:99], v[194:197], v[214:217], v[96:99]
	v_mfma_f32_16x16x32_bf16 v[88:91], v[166:169], v[230:233], v[88:91]
	v_mfma_f32_16x16x32_bf16 v[80:83], v[194:197], v[230:233], v[80:83]
	v_mfma_f32_16x16x32_bf16 v[72:75], v[166:169], v[238:241], v[72:75]
	v_mfma_f32_16x16x32_bf16 v[64:67], v[194:197], v[238:241], v[64:67]
	s_barrier
; #define PG8_STAGE(bufoff, gbase, voff) do { _Pragma("unroll") for (int _i = 0; _i < 2; ++_i) \
;         __builtin_amdgcn_global_load_lds((const unsigned*)((const char*)(gbase) + (voff)[_i]), (LAS unsigned*)(lds + (bufoff) + ldsw + _i * 8192), 16, 0, 0); } while (0)
; #define PG8_LDA(dst, b, h) do { _Pragma("unroll") for (int m = 0; m < 4; ++m) _Pragma("unroll") for (int k = 0; k < 2; ++k) dst[m][k] = *(const LAS bf16x8*)(lds + PG8_SA(b, h) + aoff + m * 2048 + k * 1024); } while (0)
; #define PG8_LDB(dst, b, h) do { _Pragma("unroll") for (int n = 0; n < 2; ++n) _Pragma("unroll") for (int k = 0; k < 2; ++k) dst[n][k] = *(const LAS bf16x8*)(lds + PG8_SB(b, h) + boff + n * 2048 + k * 1024); } while (0)
; #define PG8_MMA(ai, bj, At, Bt) do { __builtin_amdgcn_s_setprio(1); _Pragma("unroll") for (int m = 0; m < 4; ++m) _Pragma("unroll") for (int n = 0; n < 2; ++n) _Pragma("unroll") for (int k = 0; k < 2; ++k) \
;         acc[ai][bj][m][n] = __builtin_amdgcn_mfma_f32_16x16x32_bf16(Bt[n][k], At[m][k], acc[ai][bj][m][n], 0, 0, 0); __builtin_amdgcn_s_setprio(0); } while (0)
; #define PG8_WAIT_V(n) asm volatile("s_waitcnt vmcnt(" #n ")" ::: "memory")
; #define PG8_BAR __builtin_amdgcn_s_barrier()
; template <class Epi>
; __device__ __forceinline__ void gemm_phase(LAS unsigned char* lds, const Gemm g, const StaticOrder& S, const Epi& E, const int tid) {
;     ...
;             PG8_LDB(B0, 0, 0); PG8_LDB(B1, 0, 1); PG8_SCHED; PG8_LDA(At, 0, 0); PG8_STAGE(PG8_SA(1, 1), a1 + hstepA, voffA);
;             PG8_WAIT_V(8); PG8_WAIT_L(0); PG8_BAR; PG8_MMA(0, 0, At, B0); PG8_MMA(0, 1, At, B1); PG8_BAR; PG8_SCHED;
;             PG8_LDA(At, 0, 1); PG8_STAGE(PG8_SB(0, 0), b2, voffB); PG8_STAGE(PG8_SB(0, 1), b2 + hstepB, voffB); PG8_STAGE(PG8_SA(0, 0), a2, voffA);
;             PG8_WAIT_V(8); PG8_WAIT_L(0); PG8_BAR; PG8_MMA(1, 0, At, B0); PG8_MMA(1, 1, At, B1); PG8_BAR; PG8_SCHED;
;             PG8_LDB(B0, 1, 0); PG8_LDB(B1, 1, 1); PG8_SCHED; PG8_LDA(At, 1, 0); PG8_STAGE(PG8_SA(0, 1), a2 + hstepA, voffA);
;             PG8_WAIT_V(8); PG8_WAIT_L(0); PG8_BAR; PG8_MMA(0, 0, At, B0); PG8_MMA(0, 1, At, B1); PG8_BAR; PG8_SCHED;
;             PG8_LDA(At, 1, 1); PG8_STAGE(PG8_SB(1, 0), b3, voffB); PG8_STAGE(PG8_SB(1, 1), b3 + hstepB, voffB); PG8_STAGE(PG8_SA(1, 0), a3, voffA);
;             PG8_WAIT_V(8); PG8_WAIT_L(0); PG8_BAR; PG8_MMA(1, 0, At, B0); PG8_MMA(1, 1, At, B1); PG8_BAR; PG8_SCHED;
	s_add_i32 s2, s56, s22
	v_lshl_add_u64 v[174:175], v[174:175], 0, s[36:37]
	s_mov_b32 m0, s2
	ds_read_b128 v[202:205], v144 offset:49152
	ds_read_b128 v[206:209], v144 offset:50176
	ds_read_b128 v[210:213], v144 offset:51200
	ds_read_b128 v[214:217], v144 offset:52224
	ds_read_b128 v[226:229], v144 offset:53248
	ds_read_b128 v[230:233], v144 offset:54272
	ds_read_b128 v[234:237], v144 offset:55296
	ds_read_b128 v[238:241], v144 offset:56320
	global_load_lds_dwordx4 v[174:175], off
	s_add_i32 m0, s2, 0x2000
	s_add_u32 s2, s34, 0x40080
	v_lshl_add_u64 v[174:175], v[178:179], 0, s[36:37]
	s_addc_u32 s3, s35, 0
	s_add_i32 s34, s57, s22
	global_load_lds_dwordx4 v[174:175], off
	v_lshl_add_u64 v[174:175], s[2:3], 0, v[176:177]
	s_mov_b32 m0, s34
	s_nop 0
	global_load_lds_dwordx4 v[174:175], off
	v_lshl_add_u64 v[174:175], s[2:3], 0, v[128:129]
	s_add_i32 m0, s34, 0x2000
	s_nop 0
	global_load_lds_dwordx4 v[174:175], off
	v_lshl_add_u64 v[174:175], v[180:181], 0, s[76:77]
	s_mov_b32 m0, s45
	s_nop 0
	global_load_lds_dwordx4 v[174:175], off
	v_lshl_add_u64 v[174:175], v[198:199], 0, s[76:77]
	s_mov_b32 m0, s46
	s_nop 0
	global_load_lds_dwordx4 v[174:175], off
	s_waitcnt vmcnt(8)
	s_waitcnt lgkmcnt(0)
	s_barrier
	v_mfma_f32_16x16x32_bf16 v[60:63], v[146:149], v[202:205], v[60:63]
	v_mfma_f32_16x16x32_bf16 v[52:55], v[154:157], v[202:205], v[52:55]
	v_mfma_f32_16x16x32_bf16 v[44:47], v[146:149], v[210:213], v[44:47]
	v_mfma_f32_16x16x32_bf16 v[36:39], v[154:157], v[210:213], v[36:39]
	v_mfma_f32_16x16x32_bf16 v[28:31], v[146:149], v[226:229], v[28:31]
	v_mfma_f32_16x16x32_bf16 v[20:23], v[154:157], v[226:229], v[20:23]
	v_mfma_f32_16x16x32_bf16 v[12:15], v[146:149], v[234:237], v[12:15]
	v_mfma_f32_16x16x32_bf16 v[4:7], v[154:157], v[234:237], v[4:7]
	v_mfma_f32_16x16x32_bf16 v[60:63], v[150:153], v[206:209], v[60:63]
	v_mfma_f32_16x16x32_bf16 v[52:55], v[158:161], v[206:209], v[52:55]
	v_mfma_f32_16x16x32_bf16 v[44:47], v[150:153], v[214:217], v[44:47]
	v_mfma_f32_16x16x32_bf16 v[36:39], v[158:161], v[214:217], v[36:39]
	v_mfma_f32_16x16x32_bf16 v[28:31], v[150:153], v[230:233], v[28:31]
	v_mfma_f32_16x16x32_bf16 v[20:23], v[158:161], v[230:233], v[20:23]
	v_mfma_f32_16x16x32_bf16 v[12:15], v[150:153], v[238:241], v[12:15]
	v_mfma_f32_16x16x32_bf16 v[4:7], v[158:161], v[238:241], v[4:7]
	v_mfma_f32_16x16x32_bf16 v[56:59], v[162:165], v[202:205], v[56:59]
	v_mfma_f32_16x16x32_bf16 v[48:51], v[170:173], v[202:205], v[48:51]
	v_mfma_f32_16x16x32_bf16 v[40:43], v[162:165], v[210:213], v[40:43]
	v_mfma_f32_16x16x32_bf16 v[32:35], v[170:173], v[210:213], v[32:35]
	v_mfma_f32_16x16x32_bf16 v[24:27], v[162:165], v[226:229], v[24:27]
	v_mfma_f32_16x16x32_bf16 v[16:19], v[170:173], v[226:229], v[16:19]
	v_mfma_f32_16x16x32_bf16 v[8:11], v[162:165], v[234:237], v[8:11]
	v_mfma_f32_16x16x32_bf16 v[0:3], v[170:173], v[234:237], v[0:3]
	v_mfma_f32_16x16x32_bf16 v[56:59], v[166:169], v[206:209], v[56:59]
	v_mfma_f32_16x16x32_bf16 v[48:51], v[194:197], v[206:209], v[48:51]
	v_mfma_f32_16x16x32_bf16 v[40:43], v[166:169], v[214:217], v[40:43]
	v_mfma_f32_16x16x32_bf16 v[32:35], v[194:197], v[214:217], v[32:35]
	v_mfma_f32_16x16x32_bf16 v[24:27], v[166:169], v[230:233], v[24:27]
	v_mfma_f32_16x16x32_bf16 v[16:19], v[194:197], v[230:233], v[16:19]
	v_mfma_f32_16x16x32_bf16 v[8:11], v[166:169], v[238:241], v[8:11]
	v_mfma_f32_16x16x32_bf16 v[0:3], v[194:197], v[238:241], v[0:3]
	s_barrier
	s_add_i32 s55, s55, 2
	s_add_u32 s53, s53, 0x100
	s_addc_u32 s54, s54, 0
	s_mov_b64 s[2:3], s[28:29]
.LBB0_453:
	s_add_u32 s28, s2, 0x1000
	s_addc_u32 s29, s3, 0
	s_add_i32 s56, 0, 0x10000
	s_cmp_eq_u32 s55, 12
	s_cselect_b32 s41, s13, s29
	s_cselect_b32 s40, s51, s28
	v_add_u32_e32 v145, s56, v143
	s_cselect_b32 s35, s11, s54
	s_cselect_b32 s34, s52, s53
	s_add_i32 s57, 0, 0x14000
	ds_read_b128 v[146:149], v145
	ds_read_b128 v[150:153], v145 offset:1024
	ds_read_b128 v[154:157], v145 offset:2048
	ds_read_b128 v[158:161], v145 offset:3072
	v_add_u32_e32 v145, s57, v143
	ds_read_b128 v[162:165], v145
	ds_read_b128 v[166:169], v145 offset:1024
	ds_read_b128 v[170:173], v145 offset:2048
	ds_read_b128 v[194:197], v145 offset:3072
	v_lshl_add_u64 v[174:175], s[2:3], 0, v[138:139]
	s_add_i32 m0, s23, 0xc000
	ds_read_b128 v[202:205], v144
	ds_read_b128 v[206:209], v144 offset:1024
	ds_read_b128 v[210:213], v144 offset:2048
	ds_read_b128 v[214:217], v144 offset:3072
	ds_read_b128 v[226:229], v144 offset:4096
	ds_read_b128 v[230:233], v144 offset:5120
	ds_read_b128 v[234:237], v144 offset:6144
	ds_read_b128 v[238:241], v144 offset:7168
	global_load_lds_dwordx4 v[174:175], off
	v_lshl_add_u64 v[174:175], s[2:3], 0, v[140:141]
	s_add_i32 m0, s23, 0xe000
	s_nop 0
	global_load_lds_dwordx4 v[174:175], off
	s_waitcnt vmcnt(8)
	s_waitcnt lgkmcnt(0)
	s_barrier
; #define PG8_STAGE(bufoff, gbase, voff) do { _Pragma("unroll") for (int _i = 0; _i < 2; ++_i) \
;         __builtin_amdgcn_global_load_lds((const unsigned*)((const char*)(gbase) + (voff)[_i]), (LAS unsigned*)(lds + (bufoff) + ldsw + _i * 8192), 16, 0, 0); } while (0)
; #define PG8_LDA(dst, b, h) do { _Pragma("unroll") for (int m = 0; m < 4; ++m) _Pragma("unroll") for (int k = 0; k < 2; ++k) dst[m][k] = *(const LAS bf16x8*)(lds + PG8_SA(b, h) + aoff + m * 2048 + k * 1024); } while (0)
; #define PG8_MMA(ai, bj, At, Bt) do { __builtin_amdgcn_s_setprio(1); _Pragma("unroll") for (int m = 0; m < 4; ++m) _Pragma("unroll") for (int n = 0; n < 2; ++n) _Pragma("unroll") for (int k = 0; k < 2; ++k) \
;         acc[ai][bj][m][n] = __builtin_amdgcn_mfma_f32_16x16x32_bf16(Bt[n][k], At[m][k], acc[ai][bj][m][n], 0, 0, 0); __builtin_amdgcn_s_setprio(0); } while (0)
; #define PG8_WAIT_V(n) asm volatile("s_waitcnt vmcnt(" #n ")" ::: "memory")
; #define PG8_WAIT_L(n) asm volatile("s_waitcnt lgkmcnt(" #n ")" ::: "memory")
; #define PG8_BAR __builtin_amdgcn_s_barrier()
; #define PG8_SCHED __builtin_amdgcn_sched_barrier(0)
; template <class Epi>
; __device__ __forceinline__ void gemm_phase(LAS unsigned char* lds, const Gemm g, const StaticOrder& S, const Epi& E, const int tid) {
;     ...
;             PG8_WAIT_V(8); PG8_WAIT_L(0); PG8_BAR; PG8_MMA(0, 0, At, B0); PG8_MMA(0, 1, At, B1); PG8_BAR; PG8_SCHED;
;             PG8_LDA(At, 0, 1); PG8_STAGE(PG8_SB(0, 0), b2, voffB); PG8_STAGE(PG8_SB(0, 1), b2 + hstepB, voffB); PG8_STAGE(PG8_SA(0, 0), a2, voffA);
;             PG8_WAIT_V(8); PG8_WAIT_L(0); PG8_BAR; PG8_MMA(1, 0, At, B0); PG8_MMA(1, 1, At, B1); PG8_BAR; PG8_SCHED;
	v_mfma_f32_16x16x32_bf16 v[124:127], v[146:149], v[202:205], v[124:127]
	v_mfma_f32_16x16x32_bf16 v[116:119], v[154:157], v[202:205], v[116:119]
	v_mfma_f32_16x16x32_bf16 v[108:111], v[146:149], v[210:213], v[108:111]
	v_mfma_f32_16x16x32_bf16 v[100:103], v[154:157], v[210:213], v[100:103]
	v_mfma_f32_16x16x32_bf16 v[92:95], v[146:149], v[226:229], v[92:95]
	v_mfma_f32_16x16x32_bf16 v[84:87], v[154:157], v[226:229], v[84:87]
	v_mfma_f32_16x16x32_bf16 v[76:79], v[146:149], v[234:237], v[76:79]
	v_mfma_f32_16x16x32_bf16 v[68:71], v[154:157], v[234:237], v[68:71]
	v_mfma_f32_16x16x32_bf16 v[124:127], v[150:153], v[206:209], v[124:127]
	v_mfma_f32_16x16x32_bf16 v[116:119], v[158:161], v[206:209], v[116:119]
	v_mfma_f32_16x16x32_bf16 v[108:111], v[150:153], v[214:217], v[108:111]
	v_mfma_f32_16x16x32_bf16 v[100:103], v[158:161], v[214:217], v[100:103]
	v_mfma_f32_16x16x32_bf16 v[92:95], v[150:153], v[230:233], v[92:95]
	v_mfma_f32_16x16x32_bf16 v[84:87], v[158:161], v[230:233], v[84:87]
	v_mfma_f32_16x16x32_bf16 v[76:79], v[150:153], v[238:241], v[76:79]
	v_mfma_f32_16x16x32_bf16 v[68:71], v[158:161], v[238:241], v[68:71]
	v_mfma_f32_16x16x32_bf16 v[120:123], v[162:165], v[202:205], v[120:123]
	v_mfma_f32_16x16x32_bf16 v[112:115], v[170:173], v[202:205], v[112:115]
	v_mfma_f32_16x16x32_bf16 v[104:107], v[162:165], v[210:213], v[104:107]
	v_mfma_f32_16x16x32_bf16 v[96:99], v[170:173], v[210:213], v[96:99]
	v_mfma_f32_16x16x32_bf16 v[88:91], v[162:165], v[226:229], v[88:91]
	v_mfma_f32_16x16x32_bf16 v[80:83], v[170:173], v[226:229], v[80:83]
	v_mfma_f32_16x16x32_bf16 v[72:75], v[162:165], v[234:237], v[72:75]
	v_mfma_f32_16x16x32_bf16 v[64:67], v[170:173], v[234:237], v[64:67]
	v_mfma_f32_16x16x32_bf16 v[120:123], v[166:169], v[206:209], v[120:123]
	v_mfma_f32_16x16x32_bf16 v[112:115], v[194:197], v[206:209], v[112:115]
	v_mfma_f32_16x16x32_bf16 v[104:107], v[166:169], v[214:217], v[104:107]
	v_mfma_f32_16x16x32_bf16 v[96:99], v[194:197], v[214:217], v[96:99]
	v_mfma_f32_16x16x32_bf16 v[88:91], v[166:169], v[230:233], v[88:91]
	v_mfma_f32_16x16x32_bf16 v[80:83], v[194:197], v[230:233], v[80:83]
	v_mfma_f32_16x16x32_bf16 v[72:75], v[166:169], v[238:241], v[72:75]
	v_mfma_f32_16x16x32_bf16 v[64:67], v[194:197], v[238:241], v[64:67]
	s_barrier
	s_add_i32 s2, s56, s22
	v_lshl_add_u64 v[174:175], s[34:35], 0, v[176:177]
	s_mov_b32 m0, s2
	ds_read_b128 v[202:205], v144 offset:16384
	ds_read_b128 v[206:209], v144 offset:17408
	ds_read_b128 v[210:213], v144 offset:18432
	ds_read_b128 v[214:217], v144 offset:19456
	ds_read_b128 v[226:229], v144 offset:20480
	ds_read_b128 v[230:233], v144 offset:21504
	ds_read_b128 v[234:237], v144 offset:22528
	ds_read_b128 v[238:241], v144 offset:23552
	global_load_lds_dwordx4 v[174:175], off
	s_add_i32 m0, s2, 0x2000
	s_add_u32 s2, s34, 0x40000
	v_lshl_add_u64 v[178:179], s[34:35], 0, v[128:129]
	s_addc_u32 s3, s35, 0
	s_add_i32 s56, s57, s22
	global_load_lds_dwordx4 v[178:179], off
	v_lshl_add_u64 v[180:181], s[2:3], 0, v[176:177]
	s_mov_b32 m0, s56
	v_lshl_add_u64 v[198:199], s[40:41], 0, v[130:131]
	global_load_lds_dwordx4 v[180:181], off
	v_lshl_add_u64 v[180:181], s[2:3], 0, v[128:129]
	s_add_i32 m0, s56, 0x2000
	s_nop 0
	global_load_lds_dwordx4 v[180:181], off
	v_lshl_add_u64 v[180:181], s[40:41], 0, v[132:133]
	s_mov_b32 m0, s23
	s_nop 0
	global_load_lds_dwordx4 v[180:181], off
	s_mov_b32 m0, s30
	s_nop 0
	global_load_lds_dwordx4 v[198:199], off
	s_waitcnt vmcnt(8)
	s_waitcnt lgkmcnt(0)
	s_barrier
	v_mfma_f32_16x16x32_bf16 v[60:63], v[146:149], v[202:205], v[60:63]
	v_mfma_f32_16x16x32_bf16 v[52:55], v[154:157], v[202:205], v[52:55]
	v_mfma_f32_16x16x32_bf16 v[44:47], v[146:149], v[210:213], v[44:47]
	v_mfma_f32_16x16x32_bf16 v[36:39], v[154:157], v[210:213], v[36:39]
	v_mfma_f32_16x16x32_bf16 v[28:31], v[146:149], v[226:229], v[28:31]
	v_mfma_f32_16x16x32_bf16 v[20:23], v[154:157], v[226:229], v[20:23]
	v_mfma_f32_16x16x32_bf16 v[12:15], v[146:149], v[234:237], v[12:15]
	v_mfma_f32_16x16x32_bf16 v[4:7], v[154:157], v[234:237], v[4:7]
	v_mfma_f32_16x16x32_bf16 v[60:63], v[150:153], v[206:209], v[60:63]
	v_mfma_f32_16x16x32_bf16 v[52:55], v[158:161], v[206:209], v[52:55]
	v_mfma_f32_16x16x32_bf16 v[44:47], v[150:153], v[214:217], v[44:47]
	v_mfma_f32_16x16x32_bf16 v[36:39], v[158:161], v[214:217], v[36:39]
	v_mfma_f32_16x16x32_bf16 v[28:31], v[150:153], v[230:233], v[28:31]
	v_mfma_f32_16x16x32_bf16 v[20:23], v[158:161], v[230:233], v[20:23]
	v_mfma_f32_16x16x32_bf16 v[12:15], v[150:153], v[238:241], v[12:15]
	v_mfma_f32_16x16x32_bf16 v[4:7], v[158:161], v[238:241], v[4:7]
	v_mfma_f32_16x16x32_bf16 v[56:59], v[162:165], v[202:205], v[56:59]
	v_mfma_f32_16x16x32_bf16 v[48:51], v[170:173], v[202:205], v[48:51]
	v_mfma_f32_16x16x32_bf16 v[40:43], v[162:165], v[210:213], v[40:43]
	v_mfma_f32_16x16x32_bf16 v[32:35], v[170:173], v[210:213], v[32:35]
	v_mfma_f32_16x16x32_bf16 v[24:27], v[162:165], v[226:229], v[24:27]
	v_mfma_f32_16x16x32_bf16 v[16:19], v[170:173], v[226:229], v[16:19]
	v_mfma_f32_16x16x32_bf16 v[8:11], v[162:165], v[234:237], v[8:11]
	v_mfma_f32_16x16x32_bf16 v[0:3], v[170:173], v[234:237], v[0:3]
	v_mfma_f32_16x16x32_bf16 v[56:59], v[166:169], v[206:209], v[56:59]
	v_mfma_f32_16x16x32_bf16 v[48:51], v[194:197], v[206:209], v[48:51]
	v_mfma_f32_16x16x32_bf16 v[40:43], v[166:169], v[214:217], v[40:43]
	v_mfma_f32_16x16x32_bf16 v[32:35], v[194:197], v[214:217], v[32:35]
	v_mfma_f32_16x16x32_bf16 v[24:27], v[166:169], v[230:233], v[24:27]
	v_mfma_f32_16x16x32_bf16 v[16:19], v[194:197], v[230:233], v[16:19]
	v_mfma_f32_16x16x32_bf16 v[8:11], v[166:169], v[238:241], v[8:11]
	v_mfma_f32_16x16x32_bf16 v[0:3], v[194:197], v[238:241], v[0:3]
	s_barrier
; #define PG8_STAGE(bufoff, gbase, voff) do { _Pragma("unroll") for (int _i = 0; _i < 2; ++_i) \
;         __builtin_amdgcn_global_load_lds((const unsigned*)((const char*)(gbase) + (voff)[_i]), (LAS unsigned*)(lds + (bufoff) + ldsw + _i * 8192), 16, 0, 0); } while (0)
; #define PG8_LDA(dst, b, h) do { _Pragma("unroll") for (int m = 0; m < 4; ++m) _Pragma("unroll") for (int k = 0; k < 2; ++k) dst[m][k] = *(const LAS bf16x8*)(lds + PG8_SA(b, h) + aoff + m * 2048 + k * 1024); } while (0)
; #define PG8_LDB(dst, b, h) do { _Pragma("unroll") for (int n = 0; n < 2; ++n) _Pragma("unroll") for (int k = 0; k < 2; ++k) dst[n][k] = *(const LAS bf16x8*)(lds + PG8_SB(b, h) + boff + n * 2048 + k * 1024); } while (0)
; #define PG8_MMA(ai, bj, At, Bt) do { __builtin_amdgcn_s_setprio(1); _Pragma("unroll") for (int m = 0; m < 4; ++m) _Pragma("unroll") for (int n = 0; n < 2; ++n) _Pragma("unroll") for (int k = 0; k < 2; ++k) \
;         acc[ai][bj][m][n] = __builtin_amdgcn_mfma_f32_16x16x32_bf16(Bt[n][k], At[m][k], acc[ai][bj][m][n], 0, 0, 0); __builtin_amdgcn_s_setprio(0); } while (0)
; #define PG8_WAIT_V(n) asm volatile("s_waitcnt vmcnt(" #n ")" ::: "memory")
; #define PG8_WAIT_L(n) asm volatile("s_waitcnt lgkmcnt(" #n ")" ::: "memory")
; #define PG8_BAR __builtin_amdgcn_s_barrier()
; #define PG8_SCHED __builtin_amdgcn_sched_barrier(0)
; template <class Epi>
; __device__ __forceinline__ void gemm_phase(LAS unsigned char* lds, const Gemm g, const StaticOrder& S, const Epi& E, const int tid) {
;     ...
;             PG8_LDB(B0, 1, 0); PG8_LDB(B1, 1, 1); PG8_SCHED; PG8_LDA(At, 1, 0); PG8_STAGE(PG8_SA(0, 1), a2 + hstepA, voffA);
;             PG8_WAIT_V(8); PG8_WAIT_L(0); PG8_BAR; PG8_MMA(0, 0, At, B0); PG8_MMA(0, 1, At, B1); PG8_BAR; PG8_SCHED;
;             PG8_LDA(At, 1, 1); PG8_STAGE(PG8_SB(1, 0), b3, voffB); PG8_STAGE(PG8_SB(1, 1), b3 + hstepB, voffB); PG8_STAGE(PG8_SA(1, 0), a3, voffA);
;             PG8_WAIT_V(8); PG8_WAIT_L(0); PG8_BAR; PG8_MMA(1, 0, At, B0); PG8_MMA(1, 1, At, B1); PG8_BAR; PG8_SCHED;
;         }
	s_add_i32 s56, 0, 0x18000
	v_add_u32_e32 v145, s56, v143
	s_add_i32 s57, 0, 0x1c000
	ds_read_b128 v[146:149], v145
	ds_read_b128 v[150:153], v145 offset:1024
	ds_read_b128 v[154:157], v145 offset:2048
	ds_read_b128 v[158:161], v145 offset:3072
	v_add_u32_e32 v145, s57, v143
	ds_read_b128 v[162:165], v145
	ds_read_b128 v[166:169], v145 offset:1024
	ds_read_b128 v[170:173], v145 offset:2048
	ds_read_b128 v[194:197], v145 offset:3072
	s_add_u32 s2, s40, 0x40000
	s_addc_u32 s3, s41, 0
	s_mov_b32 m0, s42
	v_lshl_add_u64 v[218:219], s[2:3], 0, v[132:133]
	ds_read_b128 v[202:205], v144 offset:32768
	ds_read_b128 v[206:209], v144 offset:33792
	ds_read_b128 v[210:213], v144 offset:34816
	ds_read_b128 v[214:217], v144 offset:35840
	ds_read_b128 v[226:229], v144 offset:36864
	ds_read_b128 v[230:233], v144 offset:37888
	ds_read_b128 v[234:237], v144 offset:38912
	ds_read_b128 v[238:241], v144 offset:39936
	global_load_lds_dwordx4 v[218:219], off
	v_lshl_add_u64 v[218:219], s[2:3], 0, v[130:131]
	s_mov_b32 m0, s43
	s_nop 0
	global_load_lds_dwordx4 v[218:219], off
	s_waitcnt vmcnt(8)
	s_waitcnt lgkmcnt(0)
	s_barrier
	v_mfma_f32_16x16x32_bf16 v[124:127], v[146:149], v[202:205], v[124:127]
	v_mfma_f32_16x16x32_bf16 v[116:119], v[154:157], v[202:205], v[116:119]
	v_mfma_f32_16x16x32_bf16 v[108:111], v[146:149], v[210:213], v[108:111]
	v_mfma_f32_16x16x32_bf16 v[100:103], v[154:157], v[210:213], v[100:103]
	v_mfma_f32_16x16x32_bf16 v[92:95], v[146:149], v[226:229], v[92:95]
	v_mfma_f32_16x16x32_bf16 v[84:87], v[154:157], v[226:229], v[84:87]
	v_mfma_f32_16x16x32_bf16 v[76:79], v[146:149], v[234:237], v[76:79]
	v_mfma_f32_16x16x32_bf16 v[68:71], v[154:157], v[234:237], v[68:71]
	v_mfma_f32_16x16x32_bf16 v[124:127], v[150:153], v[206:209], v[124:127]
	v_mfma_f32_16x16x32_bf16 v[116:119], v[158:161], v[206:209], v[116:119]
	v_mfma_f32_16x16x32_bf16 v[108:111], v[150:153], v[214:217], v[108:111]
	v_mfma_f32_16x16x32_bf16 v[100:103], v[158:161], v[214:217], v[100:103]
	v_mfma_f32_16x16x32_bf16 v[92:95], v[150:153], v[230:233], v[92:95]
	v_mfma_f32_16x16x32_bf16 v[84:87], v[158:161], v[230:233], v[84:87]
	v_mfma_f32_16x16x32_bf16 v[76:79], v[150:153], v[238:241], v[76:79]
	v_mfma_f32_16x16x32_bf16 v[68:71], v[158:161], v[238:241], v[68:71]
	v_mfma_f32_16x16x32_bf16 v[120:123], v[162:165], v[202:205], v[120:123]
	v_mfma_f32_16x16x32_bf16 v[112:115], v[170:173], v[202:205], v[112:115]
	v_mfma_f32_16x16x32_bf16 v[104:107], v[162:165], v[210:213], v[104:107]
	v_mfma_f32_16x16x32_bf16 v[96:99], v[170:173], v[210:213], v[96:99]
	v_mfma_f32_16x16x32_bf16 v[88:91], v[162:165], v[226:229], v[88:91]
	v_mfma_f32_16x16x32_bf16 v[80:83], v[170:173], v[226:229], v[80:83]
	v_mfma_f32_16x16x32_bf16 v[72:75], v[162:165], v[234:237], v[72:75]
	v_mfma_f32_16x16x32_bf16 v[64:67], v[170:173], v[234:237], v[64:67]
	v_mfma_f32_16x16x32_bf16 v[120:123], v[166:169], v[206:209], v[120:123]
	v_mfma_f32_16x16x32_bf16 v[112:115], v[194:197], v[206:209], v[112:115]
	v_mfma_f32_16x16x32_bf16 v[104:107], v[166:169], v[214:217], v[104:107]
	v_mfma_f32_16x16x32_bf16 v[96:99], v[194:197], v[214:217], v[96:99]
	v_mfma_f32_16x16x32_bf16 v[88:91], v[166:169], v[230:233], v[88:91]
	v_mfma_f32_16x16x32_bf16 v[80:83], v[194:197], v[230:233], v[80:83]
	v_mfma_f32_16x16x32_bf16 v[72:75], v[166:169], v[238:241], v[72:75]
	v_mfma_f32_16x16x32_bf16 v[64:67], v[194:197], v[238:241], v[64:67]
	s_barrier
	s_add_i32 s2, s56, s22
	v_lshl_add_u64 v[174:175], v[174:175], 0, s[36:37]
	s_mov_b32 m0, s2
	ds_read_b128 v[202:205], v144 offset:49152
	ds_read_b128 v[206:209], v144 offset:50176
	ds_read_b128 v[210:213], v144 offset:51200
	ds_read_b128 v[214:217], v144 offset:52224
	ds_read_b128 v[226:229], v144 offset:53248
	ds_read_b128 v[230:233], v144 offset:54272
	ds_read_b128 v[234:237], v144 offset:55296
	ds_read_b128 v[238:241], v144 offset:56320
	global_load_lds_dwordx4 v[174:175], off
	s_add_i32 m0, s2, 0x2000
	s_add_u32 s2, s34, 0x40080
	v_lshl_add_u64 v[174:175], v[178:179], 0, s[36:37]
	s_addc_u32 s3, s35, 0
	s_add_i32 s34, s57, s22
	global_load_lds_dwordx4 v[174:175], off
	v_lshl_add_u64 v[174:175], s[2:3], 0, v[176:177]
	s_mov_b32 m0, s34
	s_nop 0
	global_load_lds_dwordx4 v[174:175], off
	v_lshl_add_u64 v[174:175], s[2:3], 0, v[128:129]
	s_add_i32 m0, s34, 0x2000
	s_nop 0
	global_load_lds_dwordx4 v[174:175], off
	v_lshl_add_u64 v[174:175], v[180:181], 0, s[76:77]
	s_mov_b32 m0, s45
	s_nop 0
	global_load_lds_dwordx4 v[174:175], off
	v_lshl_add_u64 v[174:175], v[198:199], 0, s[76:77]
	s_mov_b32 m0, s46
	s_nop 0
	global_load_lds_dwordx4 v[174:175], off
	s_waitcnt vmcnt(8)
	s_waitcnt lgkmcnt(0)
	s_barrier
	v_mfma_f32_16x16x32_bf16 v[60:63], v[146:149], v[202:205], v[60:63]
	v_mfma_f32_16x16x32_bf16 v[52:55], v[154:157], v[202:205], v[52:55]
	v_mfma_f32_16x16x32_bf16 v[44:47], v[146:149], v[210:213], v[44:47]
	v_mfma_f32_16x16x32_bf16 v[36:39], v[154:157], v[210:213], v[36:39]
	v_mfma_f32_16x16x32_bf16 v[28:31], v[146:149], v[226:229], v[28:31]
	v_mfma_f32_16x16x32_bf16 v[20:23], v[154:157], v[226:229], v[20:23]
	v_mfma_f32_16x16x32_bf16 v[12:15], v[146:149], v[234:237], v[12:15]
	v_mfma_f32_16x16x32_bf16 v[4:7], v[154:157], v[234:237], v[4:7]
	v_mfma_f32_16x16x32_bf16 v[60:63], v[150:153], v[206:209], v[60:63]
	v_mfma_f32_16x16x32_bf16 v[52:55], v[158:161], v[206:209], v[52:55]
	v_mfma_f32_16x16x32_bf16 v[44:47], v[150:153], v[214:217], v[44:47]
	v_mfma_f32_16x16x32_bf16 v[36:39], v[158:161], v[214:217], v[36:39]
	v_mfma_f32_16x16x32_bf16 v[28:31], v[150:153], v[230:233], v[28:31]
	v_mfma_f32_16x16x32_bf16 v[20:23], v[158:161], v[230:233], v[20:23]
	v_mfma_f32_16x16x32_bf16 v[12:15], v[150:153], v[238:241], v[12:15]
	v_mfma_f32_16x16x32_bf16 v[4:7], v[158:161], v[238:241], v[4:7]
	v_mfma_f32_16x16x32_bf16 v[56:59], v[162:165], v[202:205], v[56:59]
	v_mfma_f32_16x16x32_bf16 v[48:51], v[170:173], v[202:205], v[48:51]
	v_mfma_f32_16x16x32_bf16 v[40:43], v[162:165], v[210:213], v[40:43]
	v_mfma_f32_16x16x32_bf16 v[32:35], v[170:173], v[210:213], v[32:35]
	v_mfma_f32_16x16x32_bf16 v[24:27], v[162:165], v[226:229], v[24:27]
	v_mfma_f32_16x16x32_bf16 v[16:19], v[170:173], v[226:229], v[16:19]
	v_mfma_f32_16x16x32_bf16 v[8:11], v[162:165], v[234:237], v[8:11]
	v_mfma_f32_16x16x32_bf16 v[0:3], v[170:173], v[234:237], v[0:3]
	v_mfma_f32_16x16x32_bf16 v[56:59], v[166:169], v[206:209], v[56:59]
	v_mfma_f32_16x16x32_bf16 v[48:51], v[194:197], v[206:209], v[48:51]
	v_mfma_f32_16x16x32_bf16 v[40:43], v[166:169], v[214:217], v[40:43]
	v_mfma_f32_16x16x32_bf16 v[32:35], v[194:197], v[214:217], v[32:35]
	v_mfma_f32_16x16x32_bf16 v[24:27], v[166:169], v[230:233], v[24:27]
	v_mfma_f32_16x16x32_bf16 v[16:19], v[194:197], v[230:233], v[16:19]
	v_mfma_f32_16x16x32_bf16 v[8:11], v[166:169], v[238:241], v[8:11]
	v_mfma_f32_16x16x32_bf16 v[0:3], v[194:197], v[238:241], v[0:3]
	s_barrier
	s_add_i32 s55, s55, 2
	s_add_u32 s53, s53, 0x100
	s_addc_u32 s54, s54, 0
	s_cmp_gt_u32 s55, 13
	s_mov_b64 s[2:3], s[28:29]
	s_cbranch_scc0 .LBB0_453
	s_and_b64 vcc, exec, s[8:9]
	s_cbranch_vccz .LBB0_456
	s_barrier
